# scan consumer ordering variant: both packed update steps ahead of the y dot-product chain in the DPP gaps
# speedup vs baseline: 1.0157x; 1.0021x over previous
.Lscan_cons_chunk:
	v_cndmask_b32_e64 v2, v4, v5, s[42:43]
	v_add_lshl_u32 v2, v2, s80, 10
	v_mov_b32_e32 v3, v180
	s_add_i32 s28, s28, 0x10000
	v_lshl_add_u64 v[2:3], v[0:1], 0, v[2:3]
	v_add_u32_e32 v5, 64, v5
	v_subrev_u32_e32 v4, 64, v4
	s_waitcnt lgkmcnt(4)
	v_fma_mix_f32 v12, v6, v20, v180 op_sel_hi:[0,1,0]
	v_fma_mix_f32 v12, v7, v20, v12 op_sel:[0,1,0] op_sel_hi:[0,1,0]
	v_fma_mix_f32 v12, v8, v21, v12 op_sel_hi:[0,1,0]
	v_fma_mix_f32 v12, v9, v21, v12 op_sel:[0,1,0] op_sel_hi:[0,1,0]
	v_pk_mul_f32 v[48:49], v[6:7], v[16:17]
	v_pk_mul_f32 v[50:51], v[8:9], v[18:19]
	v_add_f32_dpp v12, v12, v12 row_ror:1 row_mask:0xf bank_mask:0xf bound_ctrl:1
	v_pk_fma_f32 v[48:49], v[28:29], v[66:67], v[48:49] op_sel_hi:[1,0,1]
	v_pk_fma_f32 v[50:51], v[30:31], v[66:67], v[50:51] op_sel_hi:[1,0,1]
	v_add_f32_dpp v12, v12, v12 row_ror:2 row_mask:0xf bank_mask:0xf bound_ctrl:1
	s_nop 1
	v_add_f32_dpp v12, v12, v12 row_ror:4 row_mask:0xf bank_mask:0xf bound_ctrl:1
	s_nop 1
	v_add_f32_dpp v12, v12, v12 row_ror:8 row_mask:0xf bank_mask:0xf bound_ctrl:1
	v_pk_fma_f32 v[6:7], v[24:25], v[12:13], v[48:49] op_sel_hi:[1,0,1] neg_lo:[1,0,0] neg_hi:[1,0,0]
	v_pk_fma_f32 v[8:9], v[26:27], v[12:13], v[50:51] op_sel_hi:[1,0,1] neg_lo:[1,0,0] neg_hi:[1,0,0]
	ds_read_b128 v[88:91], v10 offset:2304
	ds_read_b128 v[84:87], v10 offset:2048
	ds_read_b128 v[96:99], v10 offset:2816
	ds_read_b128 v[92:95], v10 offset:2560
	s_waitcnt lgkmcnt(4)
	v_fma_mix_f32 v12, v6, v36, v180 op_sel_hi:[0,1,0]
	v_fma_mix_f32 v12, v7, v36, v12 op_sel:[0,1,0] op_sel_hi:[0,1,0]
	v_fma_mix_f32 v12, v8, v37, v12 op_sel_hi:[0,1,0]
	v_fma_mix_f32 v12, v9, v37, v12 op_sel:[0,1,0] op_sel_hi:[0,1,0]
	v_pk_mul_f32 v[48:49], v[6:7], v[32:33]
	v_pk_mul_f32 v[50:51], v[8:9], v[34:35]
	v_add_f32_dpp v12, v12, v12 row_ror:1 row_mask:0xf bank_mask:0xf bound_ctrl:1
	v_pk_fma_f32 v[48:49], v[44:45], v[66:67], v[48:49] op_sel:[0,1,0]
	v_pk_fma_f32 v[50:51], v[46:47], v[66:67], v[50:51] op_sel:[0,1,0]
	v_add_f32_dpp v12, v12, v12 row_ror:2 row_mask:0xf bank_mask:0xf bound_ctrl:1
	v_fma_mix_f32 v52, v6, v22, v180 op_sel_hi:[0,1,0]
	v_fma_mix_f32 v52, v7, v22, v52 op_sel:[0,1,0] op_sel_hi:[0,1,0]
	v_add_f32_dpp v12, v12, v12 row_ror:4 row_mask:0xf bank_mask:0xf bound_ctrl:1
	v_fma_mix_f32 v52, v8, v23, v52 op_sel_hi:[0,1,0]
	v_fma_mix_f32 v52, v9, v23, v52 op_sel:[0,1,0] op_sel_hi:[0,1,0]
	v_add_f32_dpp v12, v12, v12 row_ror:8 row_mask:0xf bank_mask:0xf bound_ctrl:1
	v_pk_fma_f32 v[6:7], v[40:41], v[12:13], v[48:49] op_sel_hi:[1,0,1] neg_lo:[1,0,0] neg_hi:[1,0,0]
	v_pk_fma_f32 v[8:9], v[42:43], v[12:13], v[50:51] op_sel_hi:[1,0,1] neg_lo:[1,0,0] neg_hi:[1,0,0]
	ds_read_b128 v[110:113], v10 offset:3328
	ds_read_b128 v[106:109], v10 offset:3072
	ds_read_b128 v[118:121], v10 offset:3840
	ds_read_b128 v[114:117], v10 offset:3584
	ds_read_b128 v[70:73], v11 offset:256
	s_waitcnt lgkmcnt(5)
	v_fma_mix_f32 v12, v6, v88, v180 op_sel_hi:[0,1,0]
	v_fma_mix_f32 v12, v7, v88, v12 op_sel:[0,1,0] op_sel_hi:[0,1,0]
	v_fma_mix_f32 v12, v8, v89, v12 op_sel_hi:[0,1,0]
	v_fma_mix_f32 v12, v9, v89, v12 op_sel:[0,1,0] op_sel_hi:[0,1,0]
	v_pk_mul_f32 v[48:49], v[6:7], v[84:85]
	v_pk_mul_f32 v[50:51], v[8:9], v[86:87]
	v_add_f32_dpp v12, v12, v12 row_ror:1 row_mask:0xf bank_mask:0xf bound_ctrl:1
	v_pk_fma_f32 v[48:49], v[96:97], v[68:69], v[48:49] op_sel_hi:[1,0,1]
	v_pk_fma_f32 v[50:51], v[98:99], v[68:69], v[50:51] op_sel_hi:[1,0,1]
	v_add_f32_dpp v12, v12, v12 row_ror:2 row_mask:0xf bank_mask:0xf bound_ctrl:1
	v_fma_mix_f32 v53, v6, v38, v180 op_sel_hi:[0,1,0]
	v_fma_mix_f32 v53, v7, v38, v53 op_sel:[0,1,0] op_sel_hi:[0,1,0]
	v_add_f32_dpp v12, v12, v12 row_ror:4 row_mask:0xf bank_mask:0xf bound_ctrl:1
	v_fma_mix_f32 v53, v8, v39, v53 op_sel_hi:[0,1,0]
	v_fma_mix_f32 v53, v9, v39, v53 op_sel:[0,1,0] op_sel_hi:[0,1,0]
	v_add_f32_dpp v12, v12, v12 row_ror:8 row_mask:0xf bank_mask:0xf bound_ctrl:1
	v_pk_fma_f32 v[6:7], v[92:93], v[12:13], v[48:49] op_sel_hi:[1,0,1] neg_lo:[1,0,0] neg_hi:[1,0,0]
	v_pk_fma_f32 v[8:9], v[94:95], v[12:13], v[50:51] op_sel_hi:[1,0,1] neg_lo:[1,0,0] neg_hi:[1,0,0]
	ds_read_b128 v[20:23], v10 offset:4352
	ds_read_b128 v[16:19], v10 offset:4096
	ds_read_b128 v[28:31], v10 offset:4864
	ds_read_b128 v[24:27], v10 offset:4608
	s_waitcnt lgkmcnt(5)
	v_fma_mix_f32 v12, v6, v110, v180 op_sel_hi:[0,1,0]
	v_fma_mix_f32 v12, v7, v110, v12 op_sel:[0,1,0] op_sel_hi:[0,1,0]
	v_fma_mix_f32 v12, v8, v111, v12 op_sel_hi:[0,1,0]
	v_fma_mix_f32 v12, v9, v111, v12 op_sel:[0,1,0] op_sel_hi:[0,1,0]
	v_pk_mul_f32 v[48:49], v[6:7], v[106:107]
	v_pk_mul_f32 v[50:51], v[8:9], v[108:109]
	v_add_f32_dpp v12, v12, v12 row_ror:1 row_mask:0xf bank_mask:0xf bound_ctrl:1
	v_pk_fma_f32 v[48:49], v[118:119], v[68:69], v[48:49] op_sel:[0,1,0]
	v_pk_fma_f32 v[50:51], v[120:121], v[68:69], v[50:51] op_sel:[0,1,0]
	v_add_f32_dpp v12, v12, v12 row_ror:2 row_mask:0xf bank_mask:0xf bound_ctrl:1
	v_fma_mix_f32 v54, v6, v90, v180 op_sel_hi:[0,1,0]
	v_fma_mix_f32 v54, v7, v90, v54 op_sel:[0,1,0] op_sel_hi:[0,1,0]
	v_add_f32_dpp v12, v12, v12 row_ror:4 row_mask:0xf bank_mask:0xf bound_ctrl:1
	v_fma_mix_f32 v54, v8, v91, v54 op_sel_hi:[0,1,0]
	v_fma_mix_f32 v54, v9, v91, v54 op_sel:[0,1,0] op_sel_hi:[0,1,0]
	v_add_f32_dpp v12, v12, v12 row_ror:8 row_mask:0xf bank_mask:0xf bound_ctrl:1
	v_pk_fma_f32 v[6:7], v[114:115], v[12:13], v[48:49] op_sel_hi:[1,0,1] neg_lo:[1,0,0] neg_hi:[1,0,0]
	v_pk_fma_f32 v[8:9], v[116:117], v[12:13], v[50:51] op_sel_hi:[1,0,1] neg_lo:[1,0,0] neg_hi:[1,0,0]
	ds_read_b128 v[36:39], v10 offset:5376
	ds_read_b128 v[32:35], v10 offset:5120
	ds_read_b128 v[44:47], v10 offset:5888
	ds_read_b128 v[40:43], v10 offset:5632
	s_waitcnt lgkmcnt(4)
	v_fma_mix_f32 v12, v6, v20, v180 op_sel_hi:[0,1,0]
	v_fma_mix_f32 v12, v7, v20, v12 op_sel:[0,1,0] op_sel_hi:[0,1,0]
	v_fma_mix_f32 v12, v8, v21, v12 op_sel_hi:[0,1,0]
	v_fma_mix_f32 v12, v9, v21, v12 op_sel:[0,1,0] op_sel_hi:[0,1,0]
	v_pk_mul_f32 v[48:49], v[6:7], v[16:17]
	v_pk_mul_f32 v[50:51], v[8:9], v[18:19]
	v_add_f32_dpp v12, v12, v12 row_ror:1 row_mask:0xf bank_mask:0xf bound_ctrl:1
	v_pk_fma_f32 v[48:49], v[28:29], v[70:71], v[48:49] op_sel_hi:[1,0,1]
	v_pk_fma_f32 v[50:51], v[30:31], v[70:71], v[50:51] op_sel_hi:[1,0,1]
	v_add_f32_dpp v12, v12, v12 row_ror:2 row_mask:0xf bank_mask:0xf bound_ctrl:1
	v_fma_mix_f32 v55, v6, v112, v180 op_sel_hi:[0,1,0]
	v_fma_mix_f32 v55, v7, v112, v55 op_sel:[0,1,0] op_sel_hi:[0,1,0]
	v_add_f32_dpp v12, v12, v12 row_ror:4 row_mask:0xf bank_mask:0xf bound_ctrl:1
	v_fma_mix_f32 v55, v8, v113, v55 op_sel_hi:[0,1,0]
	v_fma_mix_f32 v55, v9, v113, v55 op_sel:[0,1,0] op_sel_hi:[0,1,0]
	v_add_f32_dpp v12, v12, v12 row_ror:8 row_mask:0xf bank_mask:0xf bound_ctrl:1
	v_pk_fma_f32 v[6:7], v[24:25], v[12:13], v[48:49] op_sel_hi:[1,0,1] neg_lo:[1,0,0] neg_hi:[1,0,0]
	v_pk_fma_f32 v[8:9], v[26:27], v[12:13], v[50:51] op_sel_hi:[1,0,1] neg_lo:[1,0,0] neg_hi:[1,0,0]
	ds_read_b128 v[88:91], v10 offset:6400
	ds_read_b128 v[84:87], v10 offset:6144
	ds_read_b128 v[96:99], v10 offset:6912
	ds_read_b128 v[92:95], v10 offset:6656
	s_waitcnt lgkmcnt(4)
	v_fma_mix_f32 v12, v6, v36, v180 op_sel_hi:[0,1,0]
	v_fma_mix_f32 v12, v7, v36, v12 op_sel:[0,1,0] op_sel_hi:[0,1,0]
	v_fma_mix_f32 v12, v8, v37, v12 op_sel_hi:[0,1,0]
	v_fma_mix_f32 v12, v9, v37, v12 op_sel:[0,1,0] op_sel_hi:[0,1,0]
	v_pk_mul_f32 v[48:49], v[6:7], v[32:33]
	v_pk_mul_f32 v[50:51], v[8:9], v[34:35]
	v_add_f32_dpp v12, v12, v12 row_ror:1 row_mask:0xf bank_mask:0xf bound_ctrl:1
	v_pk_fma_f32 v[48:49], v[44:45], v[70:71], v[48:49] op_sel:[0,1,0]
	v_pk_fma_f32 v[50:51], v[46:47], v[70:71], v[50:51] op_sel:[0,1,0]
	v_add_f32_dpp v12, v12, v12 row_ror:2 row_mask:0xf bank_mask:0xf bound_ctrl:1
	v_fma_mix_f32 v56, v6, v22, v180 op_sel_hi:[0,1,0]
	v_fma_mix_f32 v56, v7, v22, v56 op_sel:[0,1,0] op_sel_hi:[0,1,0]
	v_add_f32_dpp v12, v12, v12 row_ror:4 row_mask:0xf bank_mask:0xf bound_ctrl:1
	v_fma_mix_f32 v56, v8, v23, v56 op_sel_hi:[0,1,0]
	v_fma_mix_f32 v56, v9, v23, v56 op_sel:[0,1,0] op_sel_hi:[0,1,0]
	v_add_f32_dpp v12, v12, v12 row_ror:8 row_mask:0xf bank_mask:0xf bound_ctrl:1
	v_pk_fma_f32 v[6:7], v[40:41], v[12:13], v[48:49] op_sel_hi:[1,0,1] neg_lo:[1,0,0] neg_hi:[1,0,0]
	v_pk_fma_f32 v[8:9], v[42:43], v[12:13], v[50:51] op_sel_hi:[1,0,1] neg_lo:[1,0,0] neg_hi:[1,0,0]
	ds_read_b128 v[110:113], v10 offset:7424
	ds_read_b128 v[106:109], v10 offset:7168
	ds_read_b128 v[118:121], v10 offset:7936
	ds_read_b128 v[114:117], v10 offset:7680
	ds_read_b128 v[66:69], v11 offset:512
	s_waitcnt lgkmcnt(5)
	v_fma_mix_f32 v12, v6, v88, v180 op_sel_hi:[0,1,0]
	v_fma_mix_f32 v12, v7, v88, v12 op_sel:[0,1,0] op_sel_hi:[0,1,0]
	v_fma_mix_f32 v12, v8, v89, v12 op_sel_hi:[0,1,0]
	v_fma_mix_f32 v12, v9, v89, v12 op_sel:[0,1,0] op_sel_hi:[0,1,0]
	v_pk_mul_f32 v[48:49], v[6:7], v[84:85]
	v_pk_mul_f32 v[50:51], v[8:9], v[86:87]
	v_add_f32_dpp v12, v12, v12 row_ror:1 row_mask:0xf bank_mask:0xf bound_ctrl:1
	v_pk_fma_f32 v[48:49], v[96:97], v[72:73], v[48:49] op_sel_hi:[1,0,1]
	v_pk_fma_f32 v[50:51], v[98:99], v[72:73], v[50:51] op_sel_hi:[1,0,1]
	v_add_f32_dpp v12, v12, v12 row_ror:2 row_mask:0xf bank_mask:0xf bound_ctrl:1
	v_fma_mix_f32 v57, v6, v38, v180 op_sel_hi:[0,1,0]
	v_fma_mix_f32 v57, v7, v38, v57 op_sel:[0,1,0] op_sel_hi:[0,1,0]
	v_add_f32_dpp v12, v12, v12 row_ror:4 row_mask:0xf bank_mask:0xf bound_ctrl:1
	v_fma_mix_f32 v57, v8, v39, v57 op_sel_hi:[0,1,0]
	v_fma_mix_f32 v57, v9, v39, v57 op_sel:[0,1,0] op_sel_hi:[0,1,0]
	v_add_f32_dpp v12, v12, v12 row_ror:8 row_mask:0xf bank_mask:0xf bound_ctrl:1
	v_pk_fma_f32 v[6:7], v[92:93], v[12:13], v[48:49] op_sel_hi:[1,0,1] neg_lo:[1,0,0] neg_hi:[1,0,0]
	v_pk_fma_f32 v[8:9], v[94:95], v[12:13], v[50:51] op_sel_hi:[1,0,1] neg_lo:[1,0,0] neg_hi:[1,0,0]
	ds_read_b128 v[20:23], v10 offset:8448
	ds_read_b128 v[16:19], v10 offset:8192
	ds_read_b128 v[28:31], v10 offset:8960
	ds_read_b128 v[24:27], v10 offset:8704
	s_waitcnt lgkmcnt(5)
	v_fma_mix_f32 v12, v6, v110, v180 op_sel_hi:[0,1,0]
	v_fma_mix_f32 v12, v7, v110, v12 op_sel:[0,1,0] op_sel_hi:[0,1,0]
	v_fma_mix_f32 v12, v8, v111, v12 op_sel_hi:[0,1,0]
	v_fma_mix_f32 v12, v9, v111, v12 op_sel:[0,1,0] op_sel_hi:[0,1,0]
	v_pk_mul_f32 v[48:49], v[6:7], v[106:107]
	v_pk_mul_f32 v[50:51], v[8:9], v[108:109]
	v_add_f32_dpp v12, v12, v12 row_ror:1 row_mask:0xf bank_mask:0xf bound_ctrl:1
	v_pk_fma_f32 v[48:49], v[118:119], v[72:73], v[48:49] op_sel:[0,1,0]
	v_pk_fma_f32 v[50:51], v[120:121], v[72:73], v[50:51] op_sel:[0,1,0]
	v_add_f32_dpp v12, v12, v12 row_ror:2 row_mask:0xf bank_mask:0xf bound_ctrl:1
	v_fma_mix_f32 v81, v6, v90, v180 op_sel_hi:[0,1,0]
	v_fma_mix_f32 v81, v7, v90, v81 op_sel:[0,1,0] op_sel_hi:[0,1,0]
	v_add_f32_dpp v12, v12, v12 row_ror:4 row_mask:0xf bank_mask:0xf bound_ctrl:1
	v_fma_mix_f32 v81, v8, v91, v81 op_sel_hi:[0,1,0]
	v_fma_mix_f32 v81, v9, v91, v81 op_sel:[0,1,0] op_sel_hi:[0,1,0]
	v_add_f32_dpp v12, v12, v12 row_ror:8 row_mask:0xf bank_mask:0xf bound_ctrl:1
	v_pk_fma_f32 v[6:7], v[114:115], v[12:13], v[48:49] op_sel_hi:[1,0,1] neg_lo:[1,0,0] neg_hi:[1,0,0]
	v_pk_fma_f32 v[8:9], v[116:117], v[12:13], v[50:51] op_sel_hi:[1,0,1] neg_lo:[1,0,0] neg_hi:[1,0,0]
	ds_read_b128 v[36:39], v10 offset:9472
	ds_read_b128 v[32:35], v10 offset:9216
	ds_read_b128 v[44:47], v10 offset:9984
	ds_read_b128 v[40:43], v10 offset:9728
	s_waitcnt lgkmcnt(4)
	v_fma_mix_f32 v12, v6, v20, v180 op_sel_hi:[0,1,0]
	v_fma_mix_f32 v12, v7, v20, v12 op_sel:[0,1,0] op_sel_hi:[0,1,0]
	v_fma_mix_f32 v12, v8, v21, v12 op_sel_hi:[0,1,0]
	v_fma_mix_f32 v12, v9, v21, v12 op_sel:[0,1,0] op_sel_hi:[0,1,0]
	v_pk_mul_f32 v[48:49], v[6:7], v[16:17]
	v_pk_mul_f32 v[50:51], v[8:9], v[18:19]
	v_add_f32_dpp v12, v12, v12 row_ror:1 row_mask:0xf bank_mask:0xf bound_ctrl:1
	v_pk_fma_f32 v[48:49], v[28:29], v[66:67], v[48:49] op_sel_hi:[1,0,1]
	v_pk_fma_f32 v[50:51], v[30:31], v[66:67], v[50:51] op_sel_hi:[1,0,1]
	v_add_f32_dpp v12, v12, v12 row_ror:2 row_mask:0xf bank_mask:0xf bound_ctrl:1
	v_fma_mix_f32 v82, v6, v112, v180 op_sel_hi:[0,1,0]
	v_fma_mix_f32 v82, v7, v112, v82 op_sel:[0,1,0] op_sel_hi:[0,1,0]
	v_add_f32_dpp v12, v12, v12 row_ror:4 row_mask:0xf bank_mask:0xf bound_ctrl:1
	v_fma_mix_f32 v82, v8, v113, v82 op_sel_hi:[0,1,0]
	v_fma_mix_f32 v82, v9, v113, v82 op_sel:[0,1,0] op_sel_hi:[0,1,0]
	v_add_f32_dpp v12, v12, v12 row_ror:8 row_mask:0xf bank_mask:0xf bound_ctrl:1
	v_pk_fma_f32 v[6:7], v[24:25], v[12:13], v[48:49] op_sel_hi:[1,0,1] neg_lo:[1,0,0] neg_hi:[1,0,0]
	v_pk_fma_f32 v[8:9], v[26:27], v[12:13], v[50:51] op_sel_hi:[1,0,1] neg_lo:[1,0,0] neg_hi:[1,0,0]
	ds_read_b128 v[88:91], v10 offset:10496
	ds_read_b128 v[84:87], v10 offset:10240
	ds_read_b128 v[96:99], v10 offset:11008
	ds_read_b128 v[92:95], v10 offset:10752
	s_waitcnt lgkmcnt(4)
	v_fma_mix_f32 v12, v6, v36, v180 op_sel_hi:[0,1,0]
	v_fma_mix_f32 v12, v7, v36, v12 op_sel:[0,1,0] op_sel_hi:[0,1,0]
	v_fma_mix_f32 v12, v8, v37, v12 op_sel_hi:[0,1,0]
	v_fma_mix_f32 v12, v9, v37, v12 op_sel:[0,1,0] op_sel_hi:[0,1,0]
	v_pk_mul_f32 v[48:49], v[6:7], v[32:33]
	v_pk_mul_f32 v[50:51], v[8:9], v[34:35]
	v_add_f32_dpp v12, v12, v12 row_ror:1 row_mask:0xf bank_mask:0xf bound_ctrl:1
	v_pk_fma_f32 v[48:49], v[44:45], v[66:67], v[48:49] op_sel:[0,1,0]
	v_pk_fma_f32 v[50:51], v[46:47], v[66:67], v[50:51] op_sel:[0,1,0]
	v_add_f32_dpp v12, v12, v12 row_ror:2 row_mask:0xf bank_mask:0xf bound_ctrl:1
	v_fma_mix_f32 v83, v6, v22, v180 op_sel_hi:[0,1,0]
	v_fma_mix_f32 v83, v7, v22, v83 op_sel:[0,1,0] op_sel_hi:[0,1,0]
	v_add_f32_dpp v12, v12, v12 row_ror:4 row_mask:0xf bank_mask:0xf bound_ctrl:1
	v_fma_mix_f32 v83, v8, v23, v83 op_sel_hi:[0,1,0]
	v_fma_mix_f32 v83, v9, v23, v83 op_sel:[0,1,0] op_sel_hi:[0,1,0]
	v_add_f32_dpp v12, v12, v12 row_ror:8 row_mask:0xf bank_mask:0xf bound_ctrl:1
	v_pk_fma_f32 v[6:7], v[40:41], v[12:13], v[48:49] op_sel_hi:[1,0,1] neg_lo:[1,0,0] neg_hi:[1,0,0]
	v_pk_fma_f32 v[8:9], v[42:43], v[12:13], v[50:51] op_sel_hi:[1,0,1] neg_lo:[1,0,0] neg_hi:[1,0,0]
	ds_read_b128 v[110:113], v10 offset:11520
	ds_read_b128 v[106:109], v10 offset:11264
	ds_read_b128 v[118:121], v10 offset:12032
	ds_read_b128 v[114:117], v10 offset:11776
	ds_read_b128 v[70:73], v11 offset:768
	s_waitcnt lgkmcnt(5)
	v_fma_mix_f32 v12, v6, v88, v180 op_sel_hi:[0,1,0]
	v_fma_mix_f32 v12, v7, v88, v12 op_sel:[0,1,0] op_sel_hi:[0,1,0]
	v_fma_mix_f32 v12, v8, v89, v12 op_sel_hi:[0,1,0]
	v_fma_mix_f32 v12, v9, v89, v12 op_sel:[0,1,0] op_sel_hi:[0,1,0]
	v_pk_mul_f32 v[48:49], v[6:7], v[84:85]
	v_pk_mul_f32 v[50:51], v[8:9], v[86:87]
	v_add_f32_dpp v12, v12, v12 row_ror:1 row_mask:0xf bank_mask:0xf bound_ctrl:1
	v_pk_fma_f32 v[48:49], v[96:97], v[68:69], v[48:49] op_sel_hi:[1,0,1]
	v_pk_fma_f32 v[50:51], v[98:99], v[68:69], v[50:51] op_sel_hi:[1,0,1]
	v_add_f32_dpp v12, v12, v12 row_ror:2 row_mask:0xf bank_mask:0xf bound_ctrl:1
	v_fma_mix_f32 v100, v6, v38, v180 op_sel_hi:[0,1,0]
	v_fma_mix_f32 v100, v7, v38, v100 op_sel:[0,1,0] op_sel_hi:[0,1,0]
	v_add_f32_dpp v12, v12, v12 row_ror:4 row_mask:0xf bank_mask:0xf bound_ctrl:1
	v_fma_mix_f32 v100, v8, v39, v100 op_sel_hi:[0,1,0]
	v_fma_mix_f32 v100, v9, v39, v100 op_sel:[0,1,0] op_sel_hi:[0,1,0]
	v_add_f32_dpp v12, v12, v12 row_ror:8 row_mask:0xf bank_mask:0xf bound_ctrl:1
	v_pk_fma_f32 v[6:7], v[92:93], v[12:13], v[48:49] op_sel_hi:[1,0,1] neg_lo:[1,0,0] neg_hi:[1,0,0]
	v_pk_fma_f32 v[8:9], v[94:95], v[12:13], v[50:51] op_sel_hi:[1,0,1] neg_lo:[1,0,0] neg_hi:[1,0,0]
	ds_read_b128 v[20:23], v10 offset:12544
	ds_read_b128 v[16:19], v10 offset:12288
	ds_read_b128 v[28:31], v10 offset:13056
	ds_read_b128 v[24:27], v10 offset:12800
	s_waitcnt lgkmcnt(5)
	v_fma_mix_f32 v12, v6, v110, v180 op_sel_hi:[0,1,0]
	v_fma_mix_f32 v12, v7, v110, v12 op_sel:[0,1,0] op_sel_hi:[0,1,0]
	v_fma_mix_f32 v12, v8, v111, v12 op_sel_hi:[0,1,0]
	v_fma_mix_f32 v12, v9, v111, v12 op_sel:[0,1,0] op_sel_hi:[0,1,0]
	v_pk_mul_f32 v[48:49], v[6:7], v[106:107]
	v_pk_mul_f32 v[50:51], v[8:9], v[108:109]
	v_add_f32_dpp v12, v12, v12 row_ror:1 row_mask:0xf bank_mask:0xf bound_ctrl:1
	v_pk_fma_f32 v[48:49], v[118:119], v[68:69], v[48:49] op_sel:[0,1,0]
	v_pk_fma_f32 v[50:51], v[120:121], v[68:69], v[50:51] op_sel:[0,1,0]
	v_add_f32_dpp v12, v12, v12 row_ror:2 row_mask:0xf bank_mask:0xf bound_ctrl:1
	v_fma_mix_f32 v101, v6, v90, v180 op_sel_hi:[0,1,0]
	v_fma_mix_f32 v101, v7, v90, v101 op_sel:[0,1,0] op_sel_hi:[0,1,0]
	v_add_f32_dpp v12, v12, v12 row_ror:4 row_mask:0xf bank_mask:0xf bound_ctrl:1
	v_fma_mix_f32 v101, v8, v91, v101 op_sel_hi:[0,1,0]
	v_fma_mix_f32 v101, v9, v91, v101 op_sel:[0,1,0] op_sel_hi:[0,1,0]
	v_add_f32_dpp v12, v12, v12 row_ror:8 row_mask:0xf bank_mask:0xf bound_ctrl:1
	v_pk_fma_f32 v[6:7], v[114:115], v[12:13], v[48:49] op_sel_hi:[1,0,1] neg_lo:[1,0,0] neg_hi:[1,0,0]
	v_pk_fma_f32 v[8:9], v[116:117], v[12:13], v[50:51] op_sel_hi:[1,0,1] neg_lo:[1,0,0] neg_hi:[1,0,0]
	ds_read_b128 v[36:39], v10 offset:13568
	ds_read_b128 v[32:35], v10 offset:13312
	ds_read_b128 v[44:47], v10 offset:14080
	ds_read_b128 v[40:43], v10 offset:13824
	s_waitcnt lgkmcnt(4)
	v_fma_mix_f32 v12, v6, v20, v180 op_sel_hi:[0,1,0]
	v_fma_mix_f32 v12, v7, v20, v12 op_sel:[0,1,0] op_sel_hi:[0,1,0]
	v_fma_mix_f32 v12, v8, v21, v12 op_sel_hi:[0,1,0]
	v_fma_mix_f32 v12, v9, v21, v12 op_sel:[0,1,0] op_sel_hi:[0,1,0]
	v_pk_mul_f32 v[48:49], v[6:7], v[16:17]
	v_pk_mul_f32 v[50:51], v[8:9], v[18:19]
	v_add_f32_dpp v12, v12, v12 row_ror:1 row_mask:0xf bank_mask:0xf bound_ctrl:1
	v_pk_fma_f32 v[48:49], v[28:29], v[70:71], v[48:49] op_sel_hi:[1,0,1]
	v_pk_fma_f32 v[50:51], v[30:31], v[70:71], v[50:51] op_sel_hi:[1,0,1]
	v_add_f32_dpp v12, v12, v12 row_ror:2 row_mask:0xf bank_mask:0xf bound_ctrl:1
	v_fma_mix_f32 v102, v6, v112, v180 op_sel_hi:[0,1,0]
	v_fma_mix_f32 v102, v7, v112, v102 op_sel:[0,1,0] op_sel_hi:[0,1,0]
	v_add_f32_dpp v12, v12, v12 row_ror:4 row_mask:0xf bank_mask:0xf bound_ctrl:1
	v_fma_mix_f32 v102, v8, v113, v102 op_sel_hi:[0,1,0]
	v_fma_mix_f32 v102, v9, v113, v102 op_sel:[0,1,0] op_sel_hi:[0,1,0]
	v_add_f32_dpp v12, v12, v12 row_ror:8 row_mask:0xf bank_mask:0xf bound_ctrl:1
	v_pk_fma_f32 v[6:7], v[24:25], v[12:13], v[48:49] op_sel_hi:[1,0,1] neg_lo:[1,0,0] neg_hi:[1,0,0]
	v_pk_fma_f32 v[8:9], v[26:27], v[12:13], v[50:51] op_sel_hi:[1,0,1] neg_lo:[1,0,0] neg_hi:[1,0,0]
	ds_read_b128 v[88:91], v10 offset:14592
	ds_read_b128 v[84:87], v10 offset:14336
	ds_read_b128 v[96:99], v10 offset:15104
	ds_read_b128 v[92:95], v10 offset:14848
	s_waitcnt lgkmcnt(4)
	v_fma_mix_f32 v12, v6, v36, v180 op_sel_hi:[0,1,0]
	v_fma_mix_f32 v12, v7, v36, v12 op_sel:[0,1,0] op_sel_hi:[0,1,0]
	v_fma_mix_f32 v12, v8, v37, v12 op_sel_hi:[0,1,0]
	v_fma_mix_f32 v12, v9, v37, v12 op_sel:[0,1,0] op_sel_hi:[0,1,0]
	v_pk_mul_f32 v[48:49], v[6:7], v[32:33]
	v_pk_mul_f32 v[50:51], v[8:9], v[34:35]
	v_add_f32_dpp v12, v12, v12 row_ror:1 row_mask:0xf bank_mask:0xf bound_ctrl:1
	v_pk_fma_f32 v[48:49], v[44:45], v[70:71], v[48:49] op_sel:[0,1,0]
	v_pk_fma_f32 v[50:51], v[46:47], v[70:71], v[50:51] op_sel:[0,1,0]
	v_add_f32_dpp v12, v12, v12 row_ror:2 row_mask:0xf bank_mask:0xf bound_ctrl:1
	v_fma_mix_f32 v103, v6, v22, v180 op_sel_hi:[0,1,0]
	v_fma_mix_f32 v103, v7, v22, v103 op_sel:[0,1,0] op_sel_hi:[0,1,0]
	v_add_f32_dpp v12, v12, v12 row_ror:4 row_mask:0xf bank_mask:0xf bound_ctrl:1
	v_fma_mix_f32 v103, v8, v23, v103 op_sel_hi:[0,1,0]
	v_fma_mix_f32 v103, v9, v23, v103 op_sel:[0,1,0] op_sel_hi:[0,1,0]
	v_add_f32_dpp v12, v12, v12 row_ror:8 row_mask:0xf bank_mask:0xf bound_ctrl:1
	v_pk_fma_f32 v[6:7], v[40:41], v[12:13], v[48:49] op_sel_hi:[1,0,1] neg_lo:[1,0,0] neg_hi:[1,0,0]
	v_pk_fma_f32 v[8:9], v[42:43], v[12:13], v[50:51] op_sel_hi:[1,0,1] neg_lo:[1,0,0] neg_hi:[1,0,0]
	ds_read_b128 v[110:113], v10 offset:15616
	ds_read_b128 v[106:109], v10 offset:15360
	ds_read_b128 v[118:121], v10 offset:16128
	ds_read_b128 v[114:117], v10 offset:15872
	ds_read_b128 v[66:69], v11 offset:1024
	s_waitcnt lgkmcnt(5)
	v_fma_mix_f32 v12, v6, v88, v180 op_sel_hi:[0,1,0]
	v_fma_mix_f32 v12, v7, v88, v12 op_sel:[0,1,0] op_sel_hi:[0,1,0]
	v_fma_mix_f32 v12, v8, v89, v12 op_sel_hi:[0,1,0]
	v_fma_mix_f32 v12, v9, v89, v12 op_sel:[0,1,0] op_sel_hi:[0,1,0]
	v_pk_mul_f32 v[48:49], v[6:7], v[84:85]
	v_pk_mul_f32 v[50:51], v[8:9], v[86:87]
	v_add_f32_dpp v12, v12, v12 row_ror:1 row_mask:0xf bank_mask:0xf bound_ctrl:1
	v_pk_fma_f32 v[48:49], v[96:97], v[72:73], v[48:49] op_sel_hi:[1,0,1]
	v_pk_fma_f32 v[50:51], v[98:99], v[72:73], v[50:51] op_sel_hi:[1,0,1]
	v_add_f32_dpp v12, v12, v12 row_ror:2 row_mask:0xf bank_mask:0xf bound_ctrl:1
	v_fma_mix_f32 v104, v6, v38, v180 op_sel_hi:[0,1,0]
	v_fma_mix_f32 v104, v7, v38, v104 op_sel:[0,1,0] op_sel_hi:[0,1,0]
	v_add_f32_dpp v12, v12, v12 row_ror:4 row_mask:0xf bank_mask:0xf bound_ctrl:1
	v_fma_mix_f32 v104, v8, v39, v104 op_sel_hi:[0,1,0]
	v_fma_mix_f32 v104, v9, v39, v104 op_sel:[0,1,0] op_sel_hi:[0,1,0]
	v_add_f32_dpp v12, v12, v12 row_ror:8 row_mask:0xf bank_mask:0xf bound_ctrl:1
	v_pk_fma_f32 v[6:7], v[92:93], v[12:13], v[48:49] op_sel_hi:[1,0,1] neg_lo:[1,0,0] neg_hi:[1,0,0]
	v_pk_fma_f32 v[8:9], v[94:95], v[12:13], v[50:51] op_sel_hi:[1,0,1] neg_lo:[1,0,0] neg_hi:[1,0,0]
	ds_read_b128 v[20:23], v10 offset:16640
	ds_read_b128 v[16:19], v10 offset:16384
	ds_read_b128 v[28:31], v10 offset:17152
	ds_read_b128 v[24:27], v10 offset:16896
	s_waitcnt lgkmcnt(5)
	v_fma_mix_f32 v12, v6, v110, v180 op_sel_hi:[0,1,0]
	v_fma_mix_f32 v12, v7, v110, v12 op_sel:[0,1,0] op_sel_hi:[0,1,0]
	v_fma_mix_f32 v12, v8, v111, v12 op_sel_hi:[0,1,0]
	v_fma_mix_f32 v12, v9, v111, v12 op_sel:[0,1,0] op_sel_hi:[0,1,0]
	v_pk_mul_f32 v[48:49], v[6:7], v[106:107]
	v_pk_mul_f32 v[50:51], v[8:9], v[108:109]
	v_add_f32_dpp v12, v12, v12 row_ror:1 row_mask:0xf bank_mask:0xf bound_ctrl:1
	v_pk_fma_f32 v[48:49], v[118:119], v[72:73], v[48:49] op_sel:[0,1,0]
	v_pk_fma_f32 v[50:51], v[120:121], v[72:73], v[50:51] op_sel:[0,1,0]
	v_add_f32_dpp v12, v12, v12 row_ror:2 row_mask:0xf bank_mask:0xf bound_ctrl:1
	v_fma_mix_f32 v105, v6, v90, v180 op_sel_hi:[0,1,0]
	v_fma_mix_f32 v105, v7, v90, v105 op_sel:[0,1,0] op_sel_hi:[0,1,0]
	v_add_f32_dpp v12, v12, v12 row_ror:4 row_mask:0xf bank_mask:0xf bound_ctrl:1
	v_fma_mix_f32 v105, v8, v91, v105 op_sel_hi:[0,1,0]
	v_fma_mix_f32 v105, v9, v91, v105 op_sel:[0,1,0] op_sel_hi:[0,1,0]
	v_add_f32_dpp v12, v12, v12 row_ror:8 row_mask:0xf bank_mask:0xf bound_ctrl:1
	v_pk_fma_f32 v[6:7], v[114:115], v[12:13], v[48:49] op_sel_hi:[1,0,1] neg_lo:[1,0,0] neg_hi:[1,0,0]
	v_pk_fma_f32 v[8:9], v[116:117], v[12:13], v[50:51] op_sel_hi:[1,0,1] neg_lo:[1,0,0] neg_hi:[1,0,0]
	ds_read_b128 v[36:39], v10 offset:17664
	ds_read_b128 v[32:35], v10 offset:17408
	ds_read_b128 v[44:47], v10 offset:18176
	ds_read_b128 v[40:43], v10 offset:17920
	s_waitcnt lgkmcnt(4)
	v_fma_mix_f32 v12, v6, v20, v180 op_sel_hi:[0,1,0]
	v_fma_mix_f32 v12, v7, v20, v12 op_sel:[0,1,0] op_sel_hi:[0,1,0]
	v_fma_mix_f32 v12, v8, v21, v12 op_sel_hi:[0,1,0]
	v_fma_mix_f32 v12, v9, v21, v12 op_sel:[0,1,0] op_sel_hi:[0,1,0]
	v_pk_mul_f32 v[48:49], v[6:7], v[16:17]
	v_pk_mul_f32 v[50:51], v[8:9], v[18:19]
	v_add_f32_dpp v12, v12, v12 row_ror:1 row_mask:0xf bank_mask:0xf bound_ctrl:1
	v_pk_fma_f32 v[48:49], v[28:29], v[66:67], v[48:49] op_sel_hi:[1,0,1]
	v_pk_fma_f32 v[50:51], v[30:31], v[66:67], v[50:51] op_sel_hi:[1,0,1]
	v_add_f32_dpp v12, v12, v12 row_ror:2 row_mask:0xf bank_mask:0xf bound_ctrl:1
	v_fma_mix_f32 v61, v6, v112, v180 op_sel_hi:[0,1,0]
	v_fma_mix_f32 v61, v7, v112, v61 op_sel:[0,1,0] op_sel_hi:[0,1,0]
	v_add_f32_dpp v12, v12, v12 row_ror:4 row_mask:0xf bank_mask:0xf bound_ctrl:1
	v_fma_mix_f32 v61, v8, v113, v61 op_sel_hi:[0,1,0]
	v_fma_mix_f32 v61, v9, v113, v61 op_sel:[0,1,0] op_sel_hi:[0,1,0]
	v_add_f32_dpp v12, v12, v12 row_ror:8 row_mask:0xf bank_mask:0xf bound_ctrl:1
	v_pk_fma_f32 v[6:7], v[24:25], v[12:13], v[48:49] op_sel_hi:[1,0,1] neg_lo:[1,0,0] neg_hi:[1,0,0]
	v_pk_fma_f32 v[8:9], v[26:27], v[12:13], v[50:51] op_sel_hi:[1,0,1] neg_lo:[1,0,0] neg_hi:[1,0,0]
	ds_read_b128 v[88:91], v10 offset:18688
	ds_read_b128 v[84:87], v10 offset:18432
	ds_read_b128 v[96:99], v10 offset:19200
	ds_read_b128 v[92:95], v10 offset:18944
	v_add_f32_dpp v83, v83, v83 row_ror:8 row_mask:0xf bank_mask:0xc
	v_add_f32_dpp v83, v52, v52 row_ror:8 row_mask:0xf bank_mask:0x3
	v_add_f32_dpp v100, v100, v100 row_ror:8 row_mask:0xf bank_mask:0xc
	v_add_f32_dpp v100, v53, v53 row_ror:8 row_mask:0xf bank_mask:0x3
	v_add_f32_dpp v101, v101, v101 row_ror:8 row_mask:0xf bank_mask:0xc
	v_add_f32_dpp v101, v54, v54 row_ror:8 row_mask:0xf bank_mask:0x3
	v_add_f32_dpp v102, v102, v102 row_ror:8 row_mask:0xf bank_mask:0xc
	v_add_f32_dpp v102, v55, v55 row_ror:8 row_mask:0xf bank_mask:0x3
	v_add_f32_dpp v103, v103, v103 row_ror:8 row_mask:0xf bank_mask:0xc
	v_add_f32_dpp v103, v56, v56 row_ror:8 row_mask:0xf bank_mask:0x3
	v_add_f32_dpp v104, v104, v104 row_ror:8 row_mask:0xf bank_mask:0xc
	v_add_f32_dpp v104, v57, v57 row_ror:8 row_mask:0xf bank_mask:0x3
	v_add_f32_dpp v105, v105, v105 row_ror:8 row_mask:0xf bank_mask:0xc
	v_add_f32_dpp v105, v81, v81 row_ror:8 row_mask:0xf bank_mask:0x3
	v_add_f32_dpp v61, v61, v61 row_ror:8 row_mask:0xf bank_mask:0xc
	v_add_f32_dpp v61, v82, v82 row_ror:8 row_mask:0xf bank_mask:0x3
	v_add_f32_dpp v103, v103, v103 row_ror:4 row_mask:0xf bank_mask:0xa
	v_add_f32_dpp v103, v83, v83 row_ror:12 row_mask:0xf bank_mask:0x5
	v_add_f32_dpp v104, v104, v104 row_ror:4 row_mask:0xf bank_mask:0xa
	v_add_f32_dpp v104, v100, v100 row_ror:12 row_mask:0xf bank_mask:0x5
	v_add_f32_dpp v105, v105, v105 row_ror:4 row_mask:0xf bank_mask:0xa
	v_add_f32_dpp v105, v101, v101 row_ror:12 row_mask:0xf bank_mask:0x5
	v_add_f32_dpp v61, v61, v61 row_ror:4 row_mask:0xf bank_mask:0xa
	v_add_f32_dpp v61, v102, v102 row_ror:12 row_mask:0xf bank_mask:0x5
	v_cndmask_b32_e64 v62, v105, v103, s[38:39]
	v_cndmask_b32_e64 v63, v103, v105, s[38:39]
	v_cndmask_b32_e64 v64, v61, v104, s[38:39]
	v_cndmask_b32_e64 v65, v104, v61, s[38:39]
	v_add_f32_dpp v62, v63, v62 quad_perm:[2,3,0,1] row_mask:0xf bank_mask:0xf bound_ctrl:1
	s_nop 0
	v_add_f32_dpp v63, v65, v64 quad_perm:[2,3,0,1] row_mask:0xf bank_mask:0xf bound_ctrl:1
	v_cndmask_b32_e64 v65, v63, v62, s[40:41]
	v_cndmask_b32_e64 v62, v62, v63, s[40:41]
	s_nop 1
	v_add_f32_dpp v62, v62, v65 quad_perm:[1,0,3,2] row_mask:0xf bank_mask:0xf bound_ctrl:1
	v_cvt_pk_bf16_f32 v62, v62, v62
	global_store_short v[2:3], v62, off
	v_lshl_add_u64 v[2:3], v[2:3], 0, s[84:85]
	s_waitcnt lgkmcnt(4)
	v_fma_mix_f32 v12, v6, v36, v180 op_sel_hi:[0,1,0]
	v_fma_mix_f32 v12, v7, v36, v12 op_sel:[0,1,0] op_sel_hi:[0,1,0]
	v_fma_mix_f32 v12, v8, v37, v12 op_sel_hi:[0,1,0]
	v_fma_mix_f32 v12, v9, v37, v12 op_sel:[0,1,0] op_sel_hi:[0,1,0]
	v_pk_mul_f32 v[48:49], v[6:7], v[32:33]
	v_pk_mul_f32 v[50:51], v[8:9], v[34:35]
	v_add_f32_dpp v12, v12, v12 row_ror:1 row_mask:0xf bank_mask:0xf bound_ctrl:1
	v_pk_fma_f32 v[48:49], v[44:45], v[66:67], v[48:49] op_sel:[0,1,0]
	v_pk_fma_f32 v[50:51], v[46:47], v[66:67], v[50:51] op_sel:[0,1,0]
	v_add_f32_dpp v12, v12, v12 row_ror:2 row_mask:0xf bank_mask:0xf bound_ctrl:1
	v_fma_mix_f32 v52, v6, v22, v180 op_sel_hi:[0,1,0]
	v_fma_mix_f32 v52, v7, v22, v52 op_sel:[0,1,0] op_sel_hi:[0,1,0]
	v_add_f32_dpp v12, v12, v12 row_ror:4 row_mask:0xf bank_mask:0xf bound_ctrl:1
	v_fma_mix_f32 v52, v8, v23, v52 op_sel_hi:[0,1,0]
	v_fma_mix_f32 v52, v9, v23, v52 op_sel:[0,1,0] op_sel_hi:[0,1,0]
	v_add_f32_dpp v12, v12, v12 row_ror:8 row_mask:0xf bank_mask:0xf bound_ctrl:1
	v_pk_fma_f32 v[6:7], v[40:41], v[12:13], v[48:49] op_sel_hi:[1,0,1] neg_lo:[1,0,0] neg_hi:[1,0,0]
	v_pk_fma_f32 v[8:9], v[42:43], v[12:13], v[50:51] op_sel_hi:[1,0,1] neg_lo:[1,0,0] neg_hi:[1,0,0]
	ds_read_b128 v[110:113], v10 offset:19712
	ds_read_b128 v[106:109], v10 offset:19456
	ds_read_b128 v[118:121], v10 offset:20224
	ds_read_b128 v[114:117], v10 offset:19968
	ds_read_b128 v[70:73], v11 offset:1280
	s_waitcnt lgkmcnt(5)
	v_fma_mix_f32 v12, v6, v88, v180 op_sel_hi:[0,1,0]
	v_fma_mix_f32 v12, v7, v88, v12 op_sel:[0,1,0] op_sel_hi:[0,1,0]
	v_fma_mix_f32 v12, v8, v89, v12 op_sel_hi:[0,1,0]
	v_fma_mix_f32 v12, v9, v89, v12 op_sel:[0,1,0] op_sel_hi:[0,1,0]
	v_pk_mul_f32 v[48:49], v[6:7], v[84:85]
	v_pk_mul_f32 v[50:51], v[8:9], v[86:87]
	v_add_f32_dpp v12, v12, v12 row_ror:1 row_mask:0xf bank_mask:0xf bound_ctrl:1
	v_pk_fma_f32 v[48:49], v[96:97], v[68:69], v[48:49] op_sel_hi:[1,0,1]
	v_pk_fma_f32 v[50:51], v[98:99], v[68:69], v[50:51] op_sel_hi:[1,0,1]
	v_add_f32_dpp v12, v12, v12 row_ror:2 row_mask:0xf bank_mask:0xf bound_ctrl:1
	v_fma_mix_f32 v53, v6, v38, v180 op_sel_hi:[0,1,0]
	v_fma_mix_f32 v53, v7, v38, v53 op_sel:[0,1,0] op_sel_hi:[0,1,0]
	v_add_f32_dpp v12, v12, v12 row_ror:4 row_mask:0xf bank_mask:0xf bound_ctrl:1
	v_fma_mix_f32 v53, v8, v39, v53 op_sel_hi:[0,1,0]
	v_fma_mix_f32 v53, v9, v39, v53 op_sel:[0,1,0] op_sel_hi:[0,1,0]
	v_add_f32_dpp v12, v12, v12 row_ror:8 row_mask:0xf bank_mask:0xf bound_ctrl:1
	v_pk_fma_f32 v[6:7], v[92:93], v[12:13], v[48:49] op_sel_hi:[1,0,1] neg_lo:[1,0,0] neg_hi:[1,0,0]
	v_pk_fma_f32 v[8:9], v[94:95], v[12:13], v[50:51] op_sel_hi:[1,0,1] neg_lo:[1,0,0] neg_hi:[1,0,0]
	ds_read_b128 v[20:23], v10 offset:20736
	ds_read_b128 v[16:19], v10 offset:20480
	ds_read_b128 v[28:31], v10 offset:21248
	ds_read_b128 v[24:27], v10 offset:20992
	s_waitcnt lgkmcnt(5)
	v_fma_mix_f32 v12, v6, v110, v180 op_sel_hi:[0,1,0]
	v_fma_mix_f32 v12, v7, v110, v12 op_sel:[0,1,0] op_sel_hi:[0,1,0]
	v_fma_mix_f32 v12, v8, v111, v12 op_sel_hi:[0,1,0]
	v_fma_mix_f32 v12, v9, v111, v12 op_sel:[0,1,0] op_sel_hi:[0,1,0]
	v_pk_mul_f32 v[48:49], v[6:7], v[106:107]
	v_pk_mul_f32 v[50:51], v[8:9], v[108:109]
	v_add_f32_dpp v12, v12, v12 row_ror:1 row_mask:0xf bank_mask:0xf bound_ctrl:1
	v_pk_fma_f32 v[48:49], v[118:119], v[68:69], v[48:49] op_sel:[0,1,0]
	v_pk_fma_f32 v[50:51], v[120:121], v[68:69], v[50:51] op_sel:[0,1,0]
	v_add_f32_dpp v12, v12, v12 row_ror:2 row_mask:0xf bank_mask:0xf bound_ctrl:1
	v_fma_mix_f32 v54, v6, v90, v180 op_sel_hi:[0,1,0]
	v_fma_mix_f32 v54, v7, v90, v54 op_sel:[0,1,0] op_sel_hi:[0,1,0]
	v_add_f32_dpp v12, v12, v12 row_ror:4 row_mask:0xf bank_mask:0xf bound_ctrl:1
	v_fma_mix_f32 v54, v8, v91, v54 op_sel_hi:[0,1,0]
	v_fma_mix_f32 v54, v9, v91, v54 op_sel:[0,1,0] op_sel_hi:[0,1,0]
	v_add_f32_dpp v12, v12, v12 row_ror:8 row_mask:0xf bank_mask:0xf bound_ctrl:1
	v_pk_fma_f32 v[6:7], v[114:115], v[12:13], v[48:49] op_sel_hi:[1,0,1] neg_lo:[1,0,0] neg_hi:[1,0,0]
	v_pk_fma_f32 v[8:9], v[116:117], v[12:13], v[50:51] op_sel_hi:[1,0,1] neg_lo:[1,0,0] neg_hi:[1,0,0]
	ds_read_b128 v[36:39], v10 offset:21760
	ds_read_b128 v[32:35], v10 offset:21504
	ds_read_b128 v[44:47], v10 offset:22272
	ds_read_b128 v[40:43], v10 offset:22016
	s_waitcnt lgkmcnt(4)
	v_fma_mix_f32 v12, v6, v20, v180 op_sel_hi:[0,1,0]
	v_fma_mix_f32 v12, v7, v20, v12 op_sel:[0,1,0] op_sel_hi:[0,1,0]
	v_fma_mix_f32 v12, v8, v21, v12 op_sel_hi:[0,1,0]
	v_fma_mix_f32 v12, v9, v21, v12 op_sel:[0,1,0] op_sel_hi:[0,1,0]
	v_pk_mul_f32 v[48:49], v[6:7], v[16:17]
	v_pk_mul_f32 v[50:51], v[8:9], v[18:19]
	v_add_f32_dpp v12, v12, v12 row_ror:1 row_mask:0xf bank_mask:0xf bound_ctrl:1
	v_pk_fma_f32 v[48:49], v[28:29], v[70:71], v[48:49] op_sel_hi:[1,0,1]
	v_pk_fma_f32 v[50:51], v[30:31], v[70:71], v[50:51] op_sel_hi:[1,0,1]
	v_add_f32_dpp v12, v12, v12 row_ror:2 row_mask:0xf bank_mask:0xf bound_ctrl:1
	v_fma_mix_f32 v55, v6, v112, v180 op_sel_hi:[0,1,0]
	v_fma_mix_f32 v55, v7, v112, v55 op_sel:[0,1,0] op_sel_hi:[0,1,0]
	v_add_f32_dpp v12, v12, v12 row_ror:4 row_mask:0xf bank_mask:0xf bound_ctrl:1
	v_fma_mix_f32 v55, v8, v113, v55 op_sel_hi:[0,1,0]
	v_fma_mix_f32 v55, v9, v113, v55 op_sel:[0,1,0] op_sel_hi:[0,1,0]
	v_add_f32_dpp v12, v12, v12 row_ror:8 row_mask:0xf bank_mask:0xf bound_ctrl:1
	v_pk_fma_f32 v[6:7], v[24:25], v[12:13], v[48:49] op_sel_hi:[1,0,1] neg_lo:[1,0,0] neg_hi:[1,0,0]
	v_pk_fma_f32 v[8:9], v[26:27], v[12:13], v[50:51] op_sel_hi:[1,0,1] neg_lo:[1,0,0] neg_hi:[1,0,0]
	ds_read_b128 v[88:91], v10 offset:22784
	ds_read_b128 v[84:87], v10 offset:22528
	ds_read_b128 v[96:99], v10 offset:23296
	ds_read_b128 v[92:95], v10 offset:23040
	s_waitcnt lgkmcnt(4)
	v_fma_mix_f32 v12, v6, v36, v180 op_sel_hi:[0,1,0]
	v_fma_mix_f32 v12, v7, v36, v12 op_sel:[0,1,0] op_sel_hi:[0,1,0]
	v_fma_mix_f32 v12, v8, v37, v12 op_sel_hi:[0,1,0]
	v_fma_mix_f32 v12, v9, v37, v12 op_sel:[0,1,0] op_sel_hi:[0,1,0]
	v_pk_mul_f32 v[48:49], v[6:7], v[32:33]
	v_pk_mul_f32 v[50:51], v[8:9], v[34:35]
	v_add_f32_dpp v12, v12, v12 row_ror:1 row_mask:0xf bank_mask:0xf bound_ctrl:1
	v_pk_fma_f32 v[48:49], v[44:45], v[70:71], v[48:49] op_sel:[0,1,0]
	v_pk_fma_f32 v[50:51], v[46:47], v[70:71], v[50:51] op_sel:[0,1,0]
	v_add_f32_dpp v12, v12, v12 row_ror:2 row_mask:0xf bank_mask:0xf bound_ctrl:1
	v_fma_mix_f32 v56, v6, v22, v180 op_sel_hi:[0,1,0]
	v_fma_mix_f32 v56, v7, v22, v56 op_sel:[0,1,0] op_sel_hi:[0,1,0]
	v_add_f32_dpp v12, v12, v12 row_ror:4 row_mask:0xf bank_mask:0xf bound_ctrl:1
	v_fma_mix_f32 v56, v8, v23, v56 op_sel_hi:[0,1,0]
	v_fma_mix_f32 v56, v9, v23, v56 op_sel:[0,1,0] op_sel_hi:[0,1,0]
	v_add_f32_dpp v12, v12, v12 row_ror:8 row_mask:0xf bank_mask:0xf bound_ctrl:1
	v_pk_fma_f32 v[6:7], v[40:41], v[12:13], v[48:49] op_sel_hi:[1,0,1] neg_lo:[1,0,0] neg_hi:[1,0,0]
	v_pk_fma_f32 v[8:9], v[42:43], v[12:13], v[50:51] op_sel_hi:[1,0,1] neg_lo:[1,0,0] neg_hi:[1,0,0]
	ds_read_b128 v[110:113], v10 offset:23808
	ds_read_b128 v[106:109], v10 offset:23552
	ds_read_b128 v[118:121], v10 offset:24320
	ds_read_b128 v[114:117], v10 offset:24064
	ds_read_b128 v[66:69], v11 offset:1536
	s_waitcnt lgkmcnt(5)
	v_fma_mix_f32 v12, v6, v88, v180 op_sel_hi:[0,1,0]
	v_fma_mix_f32 v12, v7, v88, v12 op_sel:[0,1,0] op_sel_hi:[0,1,0]
	v_fma_mix_f32 v12, v8, v89, v12 op_sel_hi:[0,1,0]
	v_fma_mix_f32 v12, v9, v89, v12 op_sel:[0,1,0] op_sel_hi:[0,1,0]
	v_pk_mul_f32 v[48:49], v[6:7], v[84:85]
	v_pk_mul_f32 v[50:51], v[8:9], v[86:87]
	v_add_f32_dpp v12, v12, v12 row_ror:1 row_mask:0xf bank_mask:0xf bound_ctrl:1
	v_pk_fma_f32 v[48:49], v[96:97], v[72:73], v[48:49] op_sel_hi:[1,0,1]
	v_pk_fma_f32 v[50:51], v[98:99], v[72:73], v[50:51] op_sel_hi:[1,0,1]
	v_add_f32_dpp v12, v12, v12 row_ror:2 row_mask:0xf bank_mask:0xf bound_ctrl:1
	v_fma_mix_f32 v57, v6, v38, v180 op_sel_hi:[0,1,0]
	v_fma_mix_f32 v57, v7, v38, v57 op_sel:[0,1,0] op_sel_hi:[0,1,0]
	v_add_f32_dpp v12, v12, v12 row_ror:4 row_mask:0xf bank_mask:0xf bound_ctrl:1
	v_fma_mix_f32 v57, v8, v39, v57 op_sel_hi:[0,1,0]
	v_fma_mix_f32 v57, v9, v39, v57 op_sel:[0,1,0] op_sel_hi:[0,1,0]
	v_add_f32_dpp v12, v12, v12 row_ror:8 row_mask:0xf bank_mask:0xf bound_ctrl:1
	v_pk_fma_f32 v[6:7], v[92:93], v[12:13], v[48:49] op_sel_hi:[1,0,1] neg_lo:[1,0,0] neg_hi:[1,0,0]
	v_pk_fma_f32 v[8:9], v[94:95], v[12:13], v[50:51] op_sel_hi:[1,0,1] neg_lo:[1,0,0] neg_hi:[1,0,0]
	ds_read_b128 v[20:23], v10 offset:24832
	ds_read_b128 v[16:19], v10 offset:24576
	ds_read_b128 v[28:31], v10 offset:25344
	ds_read_b128 v[24:27], v10 offset:25088
	s_waitcnt lgkmcnt(5)
	v_fma_mix_f32 v12, v6, v110, v180 op_sel_hi:[0,1,0]
	v_fma_mix_f32 v12, v7, v110, v12 op_sel:[0,1,0] op_sel_hi:[0,1,0]
	v_fma_mix_f32 v12, v8, v111, v12 op_sel_hi:[0,1,0]
	v_fma_mix_f32 v12, v9, v111, v12 op_sel:[0,1,0] op_sel_hi:[0,1,0]
	v_pk_mul_f32 v[48:49], v[6:7], v[106:107]
	v_pk_mul_f32 v[50:51], v[8:9], v[108:109]
	v_add_f32_dpp v12, v12, v12 row_ror:1 row_mask:0xf bank_mask:0xf bound_ctrl:1
	v_pk_fma_f32 v[48:49], v[118:119], v[72:73], v[48:49] op_sel:[0,1,0]
	v_pk_fma_f32 v[50:51], v[120:121], v[72:73], v[50:51] op_sel:[0,1,0]
	v_add_f32_dpp v12, v12, v12 row_ror:2 row_mask:0xf bank_mask:0xf bound_ctrl:1
	v_fma_mix_f32 v81, v6, v90, v180 op_sel_hi:[0,1,0]
	v_fma_mix_f32 v81, v7, v90, v81 op_sel:[0,1,0] op_sel_hi:[0,1,0]
	v_add_f32_dpp v12, v12, v12 row_ror:4 row_mask:0xf bank_mask:0xf bound_ctrl:1
	v_fma_mix_f32 v81, v8, v91, v81 op_sel_hi:[0,1,0]
	v_fma_mix_f32 v81, v9, v91, v81 op_sel:[0,1,0] op_sel_hi:[0,1,0]
	v_add_f32_dpp v12, v12, v12 row_ror:8 row_mask:0xf bank_mask:0xf bound_ctrl:1
	v_pk_fma_f32 v[6:7], v[114:115], v[12:13], v[48:49] op_sel_hi:[1,0,1] neg_lo:[1,0,0] neg_hi:[1,0,0]
	v_pk_fma_f32 v[8:9], v[116:117], v[12:13], v[50:51] op_sel_hi:[1,0,1] neg_lo:[1,0,0] neg_hi:[1,0,0]
	ds_read_b128 v[36:39], v10 offset:25856
	ds_read_b128 v[32:35], v10 offset:25600
	ds_read_b128 v[44:47], v10 offset:26368
	ds_read_b128 v[40:43], v10 offset:26112
	s_waitcnt lgkmcnt(4)
	v_fma_mix_f32 v12, v6, v20, v180 op_sel_hi:[0,1,0]
	v_fma_mix_f32 v12, v7, v20, v12 op_sel:[0,1,0] op_sel_hi:[0,1,0]
	v_fma_mix_f32 v12, v8, v21, v12 op_sel_hi:[0,1,0]
	v_fma_mix_f32 v12, v9, v21, v12 op_sel:[0,1,0] op_sel_hi:[0,1,0]
	v_pk_mul_f32 v[48:49], v[6:7], v[16:17]
	v_pk_mul_f32 v[50:51], v[8:9], v[18:19]
	v_add_f32_dpp v12, v12, v12 row_ror:1 row_mask:0xf bank_mask:0xf bound_ctrl:1
	v_pk_fma_f32 v[48:49], v[28:29], v[66:67], v[48:49] op_sel_hi:[1,0,1]
	v_pk_fma_f32 v[50:51], v[30:31], v[66:67], v[50:51] op_sel_hi:[1,0,1]
	v_add_f32_dpp v12, v12, v12 row_ror:2 row_mask:0xf bank_mask:0xf bound_ctrl:1
	v_fma_mix_f32 v82, v6, v112, v180 op_sel_hi:[0,1,0]
	v_fma_mix_f32 v82, v7, v112, v82 op_sel:[0,1,0] op_sel_hi:[0,1,0]
	v_add_f32_dpp v12, v12, v12 row_ror:4 row_mask:0xf bank_mask:0xf bound_ctrl:1
	v_fma_mix_f32 v82, v8, v113, v82 op_sel_hi:[0,1,0]
	v_fma_mix_f32 v82, v9, v113, v82 op_sel:[0,1,0] op_sel_hi:[0,1,0]
	v_add_f32_dpp v12, v12, v12 row_ror:8 row_mask:0xf bank_mask:0xf bound_ctrl:1
	v_pk_fma_f32 v[6:7], v[24:25], v[12:13], v[48:49] op_sel_hi:[1,0,1] neg_lo:[1,0,0] neg_hi:[1,0,0]
	v_pk_fma_f32 v[8:9], v[26:27], v[12:13], v[50:51] op_sel_hi:[1,0,1] neg_lo:[1,0,0] neg_hi:[1,0,0]
	ds_read_b128 v[88:91], v10 offset:26880
	ds_read_b128 v[84:87], v10 offset:26624
	ds_read_b128 v[96:99], v10 offset:27392
	ds_read_b128 v[92:95], v10 offset:27136
	s_waitcnt lgkmcnt(4)
	v_fma_mix_f32 v12, v6, v36, v180 op_sel_hi:[0,1,0]
	v_fma_mix_f32 v12, v7, v36, v12 op_sel:[0,1,0] op_sel_hi:[0,1,0]
	v_fma_mix_f32 v12, v8, v37, v12 op_sel_hi:[0,1,0]
	v_fma_mix_f32 v12, v9, v37, v12 op_sel:[0,1,0] op_sel_hi:[0,1,0]
	v_pk_mul_f32 v[48:49], v[6:7], v[32:33]
	v_pk_mul_f32 v[50:51], v[8:9], v[34:35]
	v_add_f32_dpp v12, v12, v12 row_ror:1 row_mask:0xf bank_mask:0xf bound_ctrl:1
	v_pk_fma_f32 v[48:49], v[44:45], v[66:67], v[48:49] op_sel:[0,1,0]
	v_pk_fma_f32 v[50:51], v[46:47], v[66:67], v[50:51] op_sel:[0,1,0]
	v_add_f32_dpp v12, v12, v12 row_ror:2 row_mask:0xf bank_mask:0xf bound_ctrl:1
	v_fma_mix_f32 v83, v6, v22, v180 op_sel_hi:[0,1,0]
	v_fma_mix_f32 v83, v7, v22, v83 op_sel:[0,1,0] op_sel_hi:[0,1,0]
	v_add_f32_dpp v12, v12, v12 row_ror:4 row_mask:0xf bank_mask:0xf bound_ctrl:1
	v_fma_mix_f32 v83, v8, v23, v83 op_sel_hi:[0,1,0]
	v_fma_mix_f32 v83, v9, v23, v83 op_sel:[0,1,0] op_sel_hi:[0,1,0]
	v_add_f32_dpp v12, v12, v12 row_ror:8 row_mask:0xf bank_mask:0xf bound_ctrl:1
	v_pk_fma_f32 v[6:7], v[40:41], v[12:13], v[48:49] op_sel_hi:[1,0,1] neg_lo:[1,0,0] neg_hi:[1,0,0]
	v_pk_fma_f32 v[8:9], v[42:43], v[12:13], v[50:51] op_sel_hi:[1,0,1] neg_lo:[1,0,0] neg_hi:[1,0,0]
	ds_read_b128 v[110:113], v10 offset:27904
	ds_read_b128 v[106:109], v10 offset:27648
	ds_read_b128 v[118:121], v10 offset:28416
	ds_read_b128 v[114:117], v10 offset:28160
	ds_read_b128 v[70:73], v11 offset:1792
	s_waitcnt lgkmcnt(5)
	v_fma_mix_f32 v12, v6, v88, v180 op_sel_hi:[0,1,0]
	v_fma_mix_f32 v12, v7, v88, v12 op_sel:[0,1,0] op_sel_hi:[0,1,0]
	v_fma_mix_f32 v12, v8, v89, v12 op_sel_hi:[0,1,0]
	v_fma_mix_f32 v12, v9, v89, v12 op_sel:[0,1,0] op_sel_hi:[0,1,0]
	v_pk_mul_f32 v[48:49], v[6:7], v[84:85]
	v_pk_mul_f32 v[50:51], v[8:9], v[86:87]
	v_add_f32_dpp v12, v12, v12 row_ror:1 row_mask:0xf bank_mask:0xf bound_ctrl:1
	v_pk_fma_f32 v[48:49], v[96:97], v[68:69], v[48:49] op_sel_hi:[1,0,1]
	v_pk_fma_f32 v[50:51], v[98:99], v[68:69], v[50:51] op_sel_hi:[1,0,1]
	v_add_f32_dpp v12, v12, v12 row_ror:2 row_mask:0xf bank_mask:0xf bound_ctrl:1
	v_fma_mix_f32 v100, v6, v38, v180 op_sel_hi:[0,1,0]
	v_fma_mix_f32 v100, v7, v38, v100 op_sel:[0,1,0] op_sel_hi:[0,1,0]
	v_add_f32_dpp v12, v12, v12 row_ror:4 row_mask:0xf bank_mask:0xf bound_ctrl:1
	v_fma_mix_f32 v100, v8, v39, v100 op_sel_hi:[0,1,0]
	v_fma_mix_f32 v100, v9, v39, v100 op_sel:[0,1,0] op_sel_hi:[0,1,0]
	v_add_f32_dpp v12, v12, v12 row_ror:8 row_mask:0xf bank_mask:0xf bound_ctrl:1
	v_pk_fma_f32 v[6:7], v[92:93], v[12:13], v[48:49] op_sel_hi:[1,0,1] neg_lo:[1,0,0] neg_hi:[1,0,0]
	v_pk_fma_f32 v[8:9], v[94:95], v[12:13], v[50:51] op_sel_hi:[1,0,1] neg_lo:[1,0,0] neg_hi:[1,0,0]
	ds_read_b128 v[20:23], v10 offset:28928
	ds_read_b128 v[16:19], v10 offset:28672
	ds_read_b128 v[28:31], v10 offset:29440
	ds_read_b128 v[24:27], v10 offset:29184
	s_waitcnt lgkmcnt(5)
	v_fma_mix_f32 v12, v6, v110, v180 op_sel_hi:[0,1,0]
	v_fma_mix_f32 v12, v7, v110, v12 op_sel:[0,1,0] op_sel_hi:[0,1,0]
	v_fma_mix_f32 v12, v8, v111, v12 op_sel_hi:[0,1,0]
	v_fma_mix_f32 v12, v9, v111, v12 op_sel:[0,1,0] op_sel_hi:[0,1,0]
	v_pk_mul_f32 v[48:49], v[6:7], v[106:107]
	v_pk_mul_f32 v[50:51], v[8:9], v[108:109]
	v_add_f32_dpp v12, v12, v12 row_ror:1 row_mask:0xf bank_mask:0xf bound_ctrl:1
	v_pk_fma_f32 v[48:49], v[118:119], v[68:69], v[48:49] op_sel:[0,1,0]
	v_pk_fma_f32 v[50:51], v[120:121], v[68:69], v[50:51] op_sel:[0,1,0]
	v_add_f32_dpp v12, v12, v12 row_ror:2 row_mask:0xf bank_mask:0xf bound_ctrl:1
	v_fma_mix_f32 v101, v6, v90, v180 op_sel_hi:[0,1,0]
	v_fma_mix_f32 v101, v7, v90, v101 op_sel:[0,1,0] op_sel_hi:[0,1,0]
	v_add_f32_dpp v12, v12, v12 row_ror:4 row_mask:0xf bank_mask:0xf bound_ctrl:1
	v_fma_mix_f32 v101, v8, v91, v101 op_sel_hi:[0,1,0]
	v_fma_mix_f32 v101, v9, v91, v101 op_sel:[0,1,0] op_sel_hi:[0,1,0]
	v_add_f32_dpp v12, v12, v12 row_ror:8 row_mask:0xf bank_mask:0xf bound_ctrl:1
	v_pk_fma_f32 v[6:7], v[114:115], v[12:13], v[48:49] op_sel_hi:[1,0,1] neg_lo:[1,0,0] neg_hi:[1,0,0]
	v_pk_fma_f32 v[8:9], v[116:117], v[12:13], v[50:51] op_sel_hi:[1,0,1] neg_lo:[1,0,0] neg_hi:[1,0,0]
	ds_read_b128 v[36:39], v10 offset:29952
	ds_read_b128 v[32:35], v10 offset:29696
	ds_read_b128 v[44:47], v10 offset:30464
	ds_read_b128 v[40:43], v10 offset:30208
	s_waitcnt lgkmcnt(4)
	v_fma_mix_f32 v12, v6, v20, v180 op_sel_hi:[0,1,0]
	v_fma_mix_f32 v12, v7, v20, v12 op_sel:[0,1,0] op_sel_hi:[0,1,0]
	v_fma_mix_f32 v12, v8, v21, v12 op_sel_hi:[0,1,0]
	v_fma_mix_f32 v12, v9, v21, v12 op_sel:[0,1,0] op_sel_hi:[0,1,0]
	v_pk_mul_f32 v[48:49], v[6:7], v[16:17]
	v_pk_mul_f32 v[50:51], v[8:9], v[18:19]
	v_add_f32_dpp v12, v12, v12 row_ror:1 row_mask:0xf bank_mask:0xf bound_ctrl:1
	v_pk_fma_f32 v[48:49], v[28:29], v[70:71], v[48:49] op_sel_hi:[1,0,1]
	v_pk_fma_f32 v[50:51], v[30:31], v[70:71], v[50:51] op_sel_hi:[1,0,1]
	v_add_f32_dpp v12, v12, v12 row_ror:2 row_mask:0xf bank_mask:0xf bound_ctrl:1
	v_fma_mix_f32 v102, v6, v112, v180 op_sel_hi:[0,1,0]
	v_fma_mix_f32 v102, v7, v112, v102 op_sel:[0,1,0] op_sel_hi:[0,1,0]
	v_add_f32_dpp v12, v12, v12 row_ror:4 row_mask:0xf bank_mask:0xf bound_ctrl:1
	v_fma_mix_f32 v102, v8, v113, v102 op_sel_hi:[0,1,0]
	v_fma_mix_f32 v102, v9, v113, v102 op_sel:[0,1,0] op_sel_hi:[0,1,0]
	v_add_f32_dpp v12, v12, v12 row_ror:8 row_mask:0xf bank_mask:0xf bound_ctrl:1
	v_pk_fma_f32 v[6:7], v[24:25], v[12:13], v[48:49] op_sel_hi:[1,0,1] neg_lo:[1,0,0] neg_hi:[1,0,0]
	v_pk_fma_f32 v[8:9], v[26:27], v[12:13], v[50:51] op_sel_hi:[1,0,1] neg_lo:[1,0,0] neg_hi:[1,0,0]
	ds_read_b128 v[88:91], v10 offset:30976
	ds_read_b128 v[84:87], v10 offset:30720
	ds_read_b128 v[96:99], v10 offset:31488
	ds_read_b128 v[92:95], v10 offset:31232
	s_waitcnt lgkmcnt(4)
	v_fma_mix_f32 v12, v6, v36, v180 op_sel_hi:[0,1,0]
	v_fma_mix_f32 v12, v7, v36, v12 op_sel:[0,1,0] op_sel_hi:[0,1,0]
	v_fma_mix_f32 v12, v8, v37, v12 op_sel_hi:[0,1,0]
	v_fma_mix_f32 v12, v9, v37, v12 op_sel:[0,1,0] op_sel_hi:[0,1,0]
	v_pk_mul_f32 v[48:49], v[6:7], v[32:33]
	v_pk_mul_f32 v[50:51], v[8:9], v[34:35]
	v_add_f32_dpp v12, v12, v12 row_ror:1 row_mask:0xf bank_mask:0xf bound_ctrl:1
	v_pk_fma_f32 v[48:49], v[44:45], v[70:71], v[48:49] op_sel:[0,1,0]
	v_pk_fma_f32 v[50:51], v[46:47], v[70:71], v[50:51] op_sel:[0,1,0]
	v_add_f32_dpp v12, v12, v12 row_ror:2 row_mask:0xf bank_mask:0xf bound_ctrl:1
	v_fma_mix_f32 v103, v6, v22, v180 op_sel_hi:[0,1,0]
	v_fma_mix_f32 v103, v7, v22, v103 op_sel:[0,1,0] op_sel_hi:[0,1,0]
	v_add_f32_dpp v12, v12, v12 row_ror:4 row_mask:0xf bank_mask:0xf bound_ctrl:1
	v_fma_mix_f32 v103, v8, v23, v103 op_sel_hi:[0,1,0]
	v_fma_mix_f32 v103, v9, v23, v103 op_sel:[0,1,0] op_sel_hi:[0,1,0]
	v_add_f32_dpp v12, v12, v12 row_ror:8 row_mask:0xf bank_mask:0xf bound_ctrl:1
	v_pk_fma_f32 v[6:7], v[40:41], v[12:13], v[48:49] op_sel_hi:[1,0,1] neg_lo:[1,0,0] neg_hi:[1,0,0]
	v_pk_fma_f32 v[8:9], v[42:43], v[12:13], v[50:51] op_sel_hi:[1,0,1] neg_lo:[1,0,0] neg_hi:[1,0,0]
	ds_read_b128 v[110:113], v10 offset:32000
	ds_read_b128 v[106:109], v10 offset:31744
	ds_read_b128 v[118:121], v10 offset:32512
	ds_read_b128 v[114:117], v10 offset:32256
	ds_read_b128 v[66:69], v11 offset:2048
	s_waitcnt lgkmcnt(5)
	v_fma_mix_f32 v12, v6, v88, v180 op_sel_hi:[0,1,0]
	v_fma_mix_f32 v12, v7, v88, v12 op_sel:[0,1,0] op_sel_hi:[0,1,0]
	v_fma_mix_f32 v12, v8, v89, v12 op_sel_hi:[0,1,0]
	v_fma_mix_f32 v12, v9, v89, v12 op_sel:[0,1,0] op_sel_hi:[0,1,0]
	v_pk_mul_f32 v[48:49], v[6:7], v[84:85]
	v_pk_mul_f32 v[50:51], v[8:9], v[86:87]
	v_add_f32_dpp v12, v12, v12 row_ror:1 row_mask:0xf bank_mask:0xf bound_ctrl:1
	v_pk_fma_f32 v[48:49], v[96:97], v[72:73], v[48:49] op_sel_hi:[1,0,1]
	v_pk_fma_f32 v[50:51], v[98:99], v[72:73], v[50:51] op_sel_hi:[1,0,1]
	v_add_f32_dpp v12, v12, v12 row_ror:2 row_mask:0xf bank_mask:0xf bound_ctrl:1
	v_fma_mix_f32 v104, v6, v38, v180 op_sel_hi:[0,1,0]
	v_fma_mix_f32 v104, v7, v38, v104 op_sel:[0,1,0] op_sel_hi:[0,1,0]
	v_add_f32_dpp v12, v12, v12 row_ror:4 row_mask:0xf bank_mask:0xf bound_ctrl:1
	v_fma_mix_f32 v104, v8, v39, v104 op_sel_hi:[0,1,0]
	v_fma_mix_f32 v104, v9, v39, v104 op_sel:[0,1,0] op_sel_hi:[0,1,0]
	v_add_f32_dpp v12, v12, v12 row_ror:8 row_mask:0xf bank_mask:0xf bound_ctrl:1
	v_pk_fma_f32 v[6:7], v[92:93], v[12:13], v[48:49] op_sel_hi:[1,0,1] neg_lo:[1,0,0] neg_hi:[1,0,0]
	v_pk_fma_f32 v[8:9], v[94:95], v[12:13], v[50:51] op_sel_hi:[1,0,1] neg_lo:[1,0,0] neg_hi:[1,0,0]
	ds_read_b128 v[20:23], v10 offset:33024
	ds_read_b128 v[16:19], v10 offset:32768
	ds_read_b128 v[28:31], v10 offset:33536
	ds_read_b128 v[24:27], v10 offset:33280
	s_waitcnt lgkmcnt(5)
	v_fma_mix_f32 v12, v6, v110, v180 op_sel_hi:[0,1,0]
	v_fma_mix_f32 v12, v7, v110, v12 op_sel:[0,1,0] op_sel_hi:[0,1,0]
	v_fma_mix_f32 v12, v8, v111, v12 op_sel_hi:[0,1,0]
	v_fma_mix_f32 v12, v9, v111, v12 op_sel:[0,1,0] op_sel_hi:[0,1,0]
	v_pk_mul_f32 v[48:49], v[6:7], v[106:107]
	v_pk_mul_f32 v[50:51], v[8:9], v[108:109]
	v_add_f32_dpp v12, v12, v12 row_ror:1 row_mask:0xf bank_mask:0xf bound_ctrl:1
	v_pk_fma_f32 v[48:49], v[118:119], v[72:73], v[48:49] op_sel:[0,1,0]
	v_pk_fma_f32 v[50:51], v[120:121], v[72:73], v[50:51] op_sel:[0,1,0]
	v_add_f32_dpp v12, v12, v12 row_ror:2 row_mask:0xf bank_mask:0xf bound_ctrl:1
	v_fma_mix_f32 v105, v6, v90, v180 op_sel_hi:[0,1,0]
	v_fma_mix_f32 v105, v7, v90, v105 op_sel:[0,1,0] op_sel_hi:[0,1,0]
	v_add_f32_dpp v12, v12, v12 row_ror:4 row_mask:0xf bank_mask:0xf bound_ctrl:1
	v_fma_mix_f32 v105, v8, v91, v105 op_sel_hi:[0,1,0]
	v_fma_mix_f32 v105, v9, v91, v105 op_sel:[0,1,0] op_sel_hi:[0,1,0]
	v_add_f32_dpp v12, v12, v12 row_ror:8 row_mask:0xf bank_mask:0xf bound_ctrl:1
	v_pk_fma_f32 v[6:7], v[114:115], v[12:13], v[48:49] op_sel_hi:[1,0,1] neg_lo:[1,0,0] neg_hi:[1,0,0]
	v_pk_fma_f32 v[8:9], v[116:117], v[12:13], v[50:51] op_sel_hi:[1,0,1] neg_lo:[1,0,0] neg_hi:[1,0,0]
	ds_read_b128 v[36:39], v10 offset:34048
	ds_read_b128 v[32:35], v10 offset:33792
	ds_read_b128 v[44:47], v10 offset:34560
	ds_read_b128 v[40:43], v10 offset:34304
	s_waitcnt lgkmcnt(4)
	v_fma_mix_f32 v12, v6, v20, v180 op_sel_hi:[0,1,0]
	v_fma_mix_f32 v12, v7, v20, v12 op_sel:[0,1,0] op_sel_hi:[0,1,0]
	v_fma_mix_f32 v12, v8, v21, v12 op_sel_hi:[0,1,0]
	v_fma_mix_f32 v12, v9, v21, v12 op_sel:[0,1,0] op_sel_hi:[0,1,0]
	v_pk_mul_f32 v[48:49], v[6:7], v[16:17]
	v_pk_mul_f32 v[50:51], v[8:9], v[18:19]
	v_add_f32_dpp v12, v12, v12 row_ror:1 row_mask:0xf bank_mask:0xf bound_ctrl:1
	v_pk_fma_f32 v[48:49], v[28:29], v[66:67], v[48:49] op_sel_hi:[1,0,1]
	v_pk_fma_f32 v[50:51], v[30:31], v[66:67], v[50:51] op_sel_hi:[1,0,1]
	v_add_f32_dpp v12, v12, v12 row_ror:2 row_mask:0xf bank_mask:0xf bound_ctrl:1
	v_fma_mix_f32 v61, v6, v112, v180 op_sel_hi:[0,1,0]
	v_fma_mix_f32 v61, v7, v112, v61 op_sel:[0,1,0] op_sel_hi:[0,1,0]
	v_add_f32_dpp v12, v12, v12 row_ror:4 row_mask:0xf bank_mask:0xf bound_ctrl:1
	v_fma_mix_f32 v61, v8, v113, v61 op_sel_hi:[0,1,0]
	v_fma_mix_f32 v61, v9, v113, v61 op_sel:[0,1,0] op_sel_hi:[0,1,0]
	v_add_f32_dpp v12, v12, v12 row_ror:8 row_mask:0xf bank_mask:0xf bound_ctrl:1
	v_pk_fma_f32 v[6:7], v[24:25], v[12:13], v[48:49] op_sel_hi:[1,0,1] neg_lo:[1,0,0] neg_hi:[1,0,0]
	v_pk_fma_f32 v[8:9], v[26:27], v[12:13], v[50:51] op_sel_hi:[1,0,1] neg_lo:[1,0,0] neg_hi:[1,0,0]
	ds_read_b128 v[88:91], v10 offset:35072
	ds_read_b128 v[84:87], v10 offset:34816
	ds_read_b128 v[96:99], v10 offset:35584
	ds_read_b128 v[92:95], v10 offset:35328
	v_add_f32_dpp v83, v83, v83 row_ror:8 row_mask:0xf bank_mask:0xc
	v_add_f32_dpp v83, v52, v52 row_ror:8 row_mask:0xf bank_mask:0x3
	v_add_f32_dpp v100, v100, v100 row_ror:8 row_mask:0xf bank_mask:0xc
	v_add_f32_dpp v100, v53, v53 row_ror:8 row_mask:0xf bank_mask:0x3
	v_add_f32_dpp v101, v101, v101 row_ror:8 row_mask:0xf bank_mask:0xc
	v_add_f32_dpp v101, v54, v54 row_ror:8 row_mask:0xf bank_mask:0x3
	v_add_f32_dpp v102, v102, v102 row_ror:8 row_mask:0xf bank_mask:0xc
	v_add_f32_dpp v102, v55, v55 row_ror:8 row_mask:0xf bank_mask:0x3
	v_add_f32_dpp v103, v103, v103 row_ror:8 row_mask:0xf bank_mask:0xc
	v_add_f32_dpp v103, v56, v56 row_ror:8 row_mask:0xf bank_mask:0x3
	v_add_f32_dpp v104, v104, v104 row_ror:8 row_mask:0xf bank_mask:0xc
	v_add_f32_dpp v104, v57, v57 row_ror:8 row_mask:0xf bank_mask:0x3
	v_add_f32_dpp v105, v105, v105 row_ror:8 row_mask:0xf bank_mask:0xc
	v_add_f32_dpp v105, v81, v81 row_ror:8 row_mask:0xf bank_mask:0x3
	v_add_f32_dpp v61, v61, v61 row_ror:8 row_mask:0xf bank_mask:0xc
	v_add_f32_dpp v61, v82, v82 row_ror:8 row_mask:0xf bank_mask:0x3
	v_add_f32_dpp v103, v103, v103 row_ror:4 row_mask:0xf bank_mask:0xa
	v_add_f32_dpp v103, v83, v83 row_ror:12 row_mask:0xf bank_mask:0x5
	v_add_f32_dpp v104, v104, v104 row_ror:4 row_mask:0xf bank_mask:0xa
	v_add_f32_dpp v104, v100, v100 row_ror:12 row_mask:0xf bank_mask:0x5
	v_add_f32_dpp v105, v105, v105 row_ror:4 row_mask:0xf bank_mask:0xa
	v_add_f32_dpp v105, v101, v101 row_ror:12 row_mask:0xf bank_mask:0x5
	v_add_f32_dpp v61, v61, v61 row_ror:4 row_mask:0xf bank_mask:0xa
	v_add_f32_dpp v61, v102, v102 row_ror:12 row_mask:0xf bank_mask:0x5
	v_cndmask_b32_e64 v62, v105, v103, s[38:39]
	v_cndmask_b32_e64 v63, v103, v105, s[38:39]
	v_cndmask_b32_e64 v64, v61, v104, s[38:39]
	v_cndmask_b32_e64 v65, v104, v61, s[38:39]
	v_add_f32_dpp v62, v63, v62 quad_perm:[2,3,0,1] row_mask:0xf bank_mask:0xf bound_ctrl:1
	s_nop 0
	v_add_f32_dpp v63, v65, v64 quad_perm:[2,3,0,1] row_mask:0xf bank_mask:0xf bound_ctrl:1
	v_cndmask_b32_e64 v65, v63, v62, s[40:41]
	v_cndmask_b32_e64 v62, v62, v63, s[40:41]
	s_nop 1
	v_add_f32_dpp v62, v62, v65 quad_perm:[1,0,3,2] row_mask:0xf bank_mask:0xf bound_ctrl:1
	v_cvt_pk_bf16_f32 v62, v62, v62
	global_store_short v[2:3], v62, off
	v_lshl_add_u64 v[2:3], v[2:3], 0, s[84:85]
	s_waitcnt lgkmcnt(4)
	v_fma_mix_f32 v12, v6, v36, v180 op_sel_hi:[0,1,0]
	v_fma_mix_f32 v12, v7, v36, v12 op_sel:[0,1,0] op_sel_hi:[0,1,0]
	v_fma_mix_f32 v12, v8, v37, v12 op_sel_hi:[0,1,0]
	v_fma_mix_f32 v12, v9, v37, v12 op_sel:[0,1,0] op_sel_hi:[0,1,0]
	v_pk_mul_f32 v[48:49], v[6:7], v[32:33]
	v_pk_mul_f32 v[50:51], v[8:9], v[34:35]
	v_add_f32_dpp v12, v12, v12 row_ror:1 row_mask:0xf bank_mask:0xf bound_ctrl:1
	v_pk_fma_f32 v[48:49], v[44:45], v[66:67], v[48:49] op_sel:[0,1,0]
	v_pk_fma_f32 v[50:51], v[46:47], v[66:67], v[50:51] op_sel:[0,1,0]
	v_add_f32_dpp v12, v12, v12 row_ror:2 row_mask:0xf bank_mask:0xf bound_ctrl:1
	v_fma_mix_f32 v52, v6, v22, v180 op_sel_hi:[0,1,0]
	v_fma_mix_f32 v52, v7, v22, v52 op_sel:[0,1,0] op_sel_hi:[0,1,0]
	v_add_f32_dpp v12, v12, v12 row_ror:4 row_mask:0xf bank_mask:0xf bound_ctrl:1
	v_fma_mix_f32 v52, v8, v23, v52 op_sel_hi:[0,1,0]
	v_fma_mix_f32 v52, v9, v23, v52 op_sel:[0,1,0] op_sel_hi:[0,1,0]
	v_add_f32_dpp v12, v12, v12 row_ror:8 row_mask:0xf bank_mask:0xf bound_ctrl:1
	v_pk_fma_f32 v[6:7], v[40:41], v[12:13], v[48:49] op_sel_hi:[1,0,1] neg_lo:[1,0,0] neg_hi:[1,0,0]
	v_pk_fma_f32 v[8:9], v[42:43], v[12:13], v[50:51] op_sel_hi:[1,0,1] neg_lo:[1,0,0] neg_hi:[1,0,0]
	ds_read_b128 v[110:113], v10 offset:36096
	ds_read_b128 v[106:109], v10 offset:35840
	ds_read_b128 v[118:121], v10 offset:36608
	ds_read_b128 v[114:117], v10 offset:36352
	ds_read_b128 v[70:73], v11 offset:2304
	s_waitcnt lgkmcnt(5)
	v_fma_mix_f32 v12, v6, v88, v180 op_sel_hi:[0,1,0]
	v_fma_mix_f32 v12, v7, v88, v12 op_sel:[0,1,0] op_sel_hi:[0,1,0]
	v_fma_mix_f32 v12, v8, v89, v12 op_sel_hi:[0,1,0]
	v_fma_mix_f32 v12, v9, v89, v12 op_sel:[0,1,0] op_sel_hi:[0,1,0]
	v_pk_mul_f32 v[48:49], v[6:7], v[84:85]
	v_pk_mul_f32 v[50:51], v[8:9], v[86:87]
	v_add_f32_dpp v12, v12, v12 row_ror:1 row_mask:0xf bank_mask:0xf bound_ctrl:1
	v_pk_fma_f32 v[48:49], v[96:97], v[68:69], v[48:49] op_sel_hi:[1,0,1]
	v_pk_fma_f32 v[50:51], v[98:99], v[68:69], v[50:51] op_sel_hi:[1,0,1]
	v_add_f32_dpp v12, v12, v12 row_ror:2 row_mask:0xf bank_mask:0xf bound_ctrl:1
	v_fma_mix_f32 v53, v6, v38, v180 op_sel_hi:[0,1,0]
	v_fma_mix_f32 v53, v7, v38, v53 op_sel:[0,1,0] op_sel_hi:[0,1,0]
	v_add_f32_dpp v12, v12, v12 row_ror:4 row_mask:0xf bank_mask:0xf bound_ctrl:1
	v_fma_mix_f32 v53, v8, v39, v53 op_sel_hi:[0,1,0]
	v_fma_mix_f32 v53, v9, v39, v53 op_sel:[0,1,0] op_sel_hi:[0,1,0]
	v_add_f32_dpp v12, v12, v12 row_ror:8 row_mask:0xf bank_mask:0xf bound_ctrl:1
	v_pk_fma_f32 v[6:7], v[92:93], v[12:13], v[48:49] op_sel_hi:[1,0,1] neg_lo:[1,0,0] neg_hi:[1,0,0]
	v_pk_fma_f32 v[8:9], v[94:95], v[12:13], v[50:51] op_sel_hi:[1,0,1] neg_lo:[1,0,0] neg_hi:[1,0,0]
	ds_read_b128 v[20:23], v10 offset:37120
	ds_read_b128 v[16:19], v10 offset:36864
	ds_read_b128 v[28:31], v10 offset:37632
	ds_read_b128 v[24:27], v10 offset:37376
	s_waitcnt lgkmcnt(5)
	v_fma_mix_f32 v12, v6, v110, v180 op_sel_hi:[0,1,0]
	v_fma_mix_f32 v12, v7, v110, v12 op_sel:[0,1,0] op_sel_hi:[0,1,0]
	v_fma_mix_f32 v12, v8, v111, v12 op_sel_hi:[0,1,0]
	v_fma_mix_f32 v12, v9, v111, v12 op_sel:[0,1,0] op_sel_hi:[0,1,0]
	v_pk_mul_f32 v[48:49], v[6:7], v[106:107]
	v_pk_mul_f32 v[50:51], v[8:9], v[108:109]
	v_add_f32_dpp v12, v12, v12 row_ror:1 row_mask:0xf bank_mask:0xf bound_ctrl:1
	v_pk_fma_f32 v[48:49], v[118:119], v[68:69], v[48:49] op_sel:[0,1,0]
	v_pk_fma_f32 v[50:51], v[120:121], v[68:69], v[50:51] op_sel:[0,1,0]
	v_add_f32_dpp v12, v12, v12 row_ror:2 row_mask:0xf bank_mask:0xf bound_ctrl:1
	v_fma_mix_f32 v54, v6, v90, v180 op_sel_hi:[0,1,0]
	v_fma_mix_f32 v54, v7, v90, v54 op_sel:[0,1,0] op_sel_hi:[0,1,0]
	v_add_f32_dpp v12, v12, v12 row_ror:4 row_mask:0xf bank_mask:0xf bound_ctrl:1
	v_fma_mix_f32 v54, v8, v91, v54 op_sel_hi:[0,1,0]
	v_fma_mix_f32 v54, v9, v91, v54 op_sel:[0,1,0] op_sel_hi:[0,1,0]
	v_add_f32_dpp v12, v12, v12 row_ror:8 row_mask:0xf bank_mask:0xf bound_ctrl:1
	v_pk_fma_f32 v[6:7], v[114:115], v[12:13], v[48:49] op_sel_hi:[1,0,1] neg_lo:[1,0,0] neg_hi:[1,0,0]
	v_pk_fma_f32 v[8:9], v[116:117], v[12:13], v[50:51] op_sel_hi:[1,0,1] neg_lo:[1,0,0] neg_hi:[1,0,0]
	ds_read_b128 v[36:39], v10 offset:38144
	ds_read_b128 v[32:35], v10 offset:37888
	ds_read_b128 v[44:47], v10 offset:38656
	ds_read_b128 v[40:43], v10 offset:38400
	s_waitcnt lgkmcnt(4)
	v_fma_mix_f32 v12, v6, v20, v180 op_sel_hi:[0,1,0]
	v_fma_mix_f32 v12, v7, v20, v12 op_sel:[0,1,0] op_sel_hi:[0,1,0]
	v_fma_mix_f32 v12, v8, v21, v12 op_sel_hi:[0,1,0]
	v_fma_mix_f32 v12, v9, v21, v12 op_sel:[0,1,0] op_sel_hi:[0,1,0]
	v_pk_mul_f32 v[48:49], v[6:7], v[16:17]
	v_pk_mul_f32 v[50:51], v[8:9], v[18:19]
	v_add_f32_dpp v12, v12, v12 row_ror:1 row_mask:0xf bank_mask:0xf bound_ctrl:1
	v_pk_fma_f32 v[48:49], v[28:29], v[70:71], v[48:49] op_sel_hi:[1,0,1]
	v_pk_fma_f32 v[50:51], v[30:31], v[70:71], v[50:51] op_sel_hi:[1,0,1]
	v_add_f32_dpp v12, v12, v12 row_ror:2 row_mask:0xf bank_mask:0xf bound_ctrl:1
	v_fma_mix_f32 v55, v6, v112, v180 op_sel_hi:[0,1,0]
	v_fma_mix_f32 v55, v7, v112, v55 op_sel:[0,1,0] op_sel_hi:[0,1,0]
	v_add_f32_dpp v12, v12, v12 row_ror:4 row_mask:0xf bank_mask:0xf bound_ctrl:1
	v_fma_mix_f32 v55, v8, v113, v55 op_sel_hi:[0,1,0]
	v_fma_mix_f32 v55, v9, v113, v55 op_sel:[0,1,0] op_sel_hi:[0,1,0]
	v_add_f32_dpp v12, v12, v12 row_ror:8 row_mask:0xf bank_mask:0xf bound_ctrl:1
	v_pk_fma_f32 v[6:7], v[24:25], v[12:13], v[48:49] op_sel_hi:[1,0,1] neg_lo:[1,0,0] neg_hi:[1,0,0]
	v_pk_fma_f32 v[8:9], v[26:27], v[12:13], v[50:51] op_sel_hi:[1,0,1] neg_lo:[1,0,0] neg_hi:[1,0,0]
	ds_read_b128 v[88:91], v10 offset:39168
	ds_read_b128 v[84:87], v10 offset:38912
	ds_read_b128 v[96:99], v10 offset:39680
	ds_read_b128 v[92:95], v10 offset:39424
	s_waitcnt lgkmcnt(4)
	v_fma_mix_f32 v12, v6, v36, v180 op_sel_hi:[0,1,0]
	v_fma_mix_f32 v12, v7, v36, v12 op_sel:[0,1,0] op_sel_hi:[0,1,0]
	v_fma_mix_f32 v12, v8, v37, v12 op_sel_hi:[0,1,0]
	v_fma_mix_f32 v12, v9, v37, v12 op_sel:[0,1,0] op_sel_hi:[0,1,0]
	v_pk_mul_f32 v[48:49], v[6:7], v[32:33]
	v_pk_mul_f32 v[50:51], v[8:9], v[34:35]
	v_add_f32_dpp v12, v12, v12 row_ror:1 row_mask:0xf bank_mask:0xf bound_ctrl:1
	v_pk_fma_f32 v[48:49], v[44:45], v[70:71], v[48:49] op_sel:[0,1,0]
	v_pk_fma_f32 v[50:51], v[46:47], v[70:71], v[50:51] op_sel:[0,1,0]
	v_add_f32_dpp v12, v12, v12 row_ror:2 row_mask:0xf bank_mask:0xf bound_ctrl:1
	v_fma_mix_f32 v56, v6, v22, v180 op_sel_hi:[0,1,0]
	v_fma_mix_f32 v56, v7, v22, v56 op_sel:[0,1,0] op_sel_hi:[0,1,0]
	v_add_f32_dpp v12, v12, v12 row_ror:4 row_mask:0xf bank_mask:0xf bound_ctrl:1
	v_fma_mix_f32 v56, v8, v23, v56 op_sel_hi:[0,1,0]
	v_fma_mix_f32 v56, v9, v23, v56 op_sel:[0,1,0] op_sel_hi:[0,1,0]
	v_add_f32_dpp v12, v12, v12 row_ror:8 row_mask:0xf bank_mask:0xf bound_ctrl:1
	v_pk_fma_f32 v[6:7], v[40:41], v[12:13], v[48:49] op_sel_hi:[1,0,1] neg_lo:[1,0,0] neg_hi:[1,0,0]
	v_pk_fma_f32 v[8:9], v[42:43], v[12:13], v[50:51] op_sel_hi:[1,0,1] neg_lo:[1,0,0] neg_hi:[1,0,0]
	ds_read_b128 v[110:113], v10 offset:40192
	ds_read_b128 v[106:109], v10 offset:39936
	ds_read_b128 v[118:121], v10 offset:40704
	ds_read_b128 v[114:117], v10 offset:40448
	ds_read_b128 v[66:69], v11 offset:2560
	s_waitcnt lgkmcnt(5)
	v_fma_mix_f32 v12, v6, v88, v180 op_sel_hi:[0,1,0]
	v_fma_mix_f32 v12, v7, v88, v12 op_sel:[0,1,0] op_sel_hi:[0,1,0]
	v_fma_mix_f32 v12, v8, v89, v12 op_sel_hi:[0,1,0]
	v_fma_mix_f32 v12, v9, v89, v12 op_sel:[0,1,0] op_sel_hi:[0,1,0]
	v_pk_mul_f32 v[48:49], v[6:7], v[84:85]
	v_pk_mul_f32 v[50:51], v[8:9], v[86:87]
	v_add_f32_dpp v12, v12, v12 row_ror:1 row_mask:0xf bank_mask:0xf bound_ctrl:1
	v_pk_fma_f32 v[48:49], v[96:97], v[72:73], v[48:49] op_sel_hi:[1,0,1]
	v_pk_fma_f32 v[50:51], v[98:99], v[72:73], v[50:51] op_sel_hi:[1,0,1]
	v_add_f32_dpp v12, v12, v12 row_ror:2 row_mask:0xf bank_mask:0xf bound_ctrl:1
	v_fma_mix_f32 v57, v6, v38, v180 op_sel_hi:[0,1,0]
	v_fma_mix_f32 v57, v7, v38, v57 op_sel:[0,1,0] op_sel_hi:[0,1,0]
	v_add_f32_dpp v12, v12, v12 row_ror:4 row_mask:0xf bank_mask:0xf bound_ctrl:1
	v_fma_mix_f32 v57, v8, v39, v57 op_sel_hi:[0,1,0]
	v_fma_mix_f32 v57, v9, v39, v57 op_sel:[0,1,0] op_sel_hi:[0,1,0]
	v_add_f32_dpp v12, v12, v12 row_ror:8 row_mask:0xf bank_mask:0xf bound_ctrl:1
	v_pk_fma_f32 v[6:7], v[92:93], v[12:13], v[48:49] op_sel_hi:[1,0,1] neg_lo:[1,0,0] neg_hi:[1,0,0]
	v_pk_fma_f32 v[8:9], v[94:95], v[12:13], v[50:51] op_sel_hi:[1,0,1] neg_lo:[1,0,0] neg_hi:[1,0,0]
	ds_read_b128 v[20:23], v10 offset:41216
	ds_read_b128 v[16:19], v10 offset:40960
	ds_read_b128 v[28:31], v10 offset:41728
	ds_read_b128 v[24:27], v10 offset:41472
	s_waitcnt lgkmcnt(5)
	v_fma_mix_f32 v12, v6, v110, v180 op_sel_hi:[0,1,0]
	v_fma_mix_f32 v12, v7, v110, v12 op_sel:[0,1,0] op_sel_hi:[0,1,0]
	v_fma_mix_f32 v12, v8, v111, v12 op_sel_hi:[0,1,0]
	v_fma_mix_f32 v12, v9, v111, v12 op_sel:[0,1,0] op_sel_hi:[0,1,0]
	v_pk_mul_f32 v[48:49], v[6:7], v[106:107]
	v_pk_mul_f32 v[50:51], v[8:9], v[108:109]
	v_add_f32_dpp v12, v12, v12 row_ror:1 row_mask:0xf bank_mask:0xf bound_ctrl:1
	v_pk_fma_f32 v[48:49], v[118:119], v[72:73], v[48:49] op_sel:[0,1,0]
	v_pk_fma_f32 v[50:51], v[120:121], v[72:73], v[50:51] op_sel:[0,1,0]
	v_add_f32_dpp v12, v12, v12 row_ror:2 row_mask:0xf bank_mask:0xf bound_ctrl:1
	v_fma_mix_f32 v81, v6, v90, v180 op_sel_hi:[0,1,0]
	v_fma_mix_f32 v81, v7, v90, v81 op_sel:[0,1,0] op_sel_hi:[0,1,0]
	v_add_f32_dpp v12, v12, v12 row_ror:4 row_mask:0xf bank_mask:0xf bound_ctrl:1
	v_fma_mix_f32 v81, v8, v91, v81 op_sel_hi:[0,1,0]
	v_fma_mix_f32 v81, v9, v91, v81 op_sel:[0,1,0] op_sel_hi:[0,1,0]
	v_add_f32_dpp v12, v12, v12 row_ror:8 row_mask:0xf bank_mask:0xf bound_ctrl:1
	v_pk_fma_f32 v[6:7], v[114:115], v[12:13], v[48:49] op_sel_hi:[1,0,1] neg_lo:[1,0,0] neg_hi:[1,0,0]
	v_pk_fma_f32 v[8:9], v[116:117], v[12:13], v[50:51] op_sel_hi:[1,0,1] neg_lo:[1,0,0] neg_hi:[1,0,0]
	ds_read_b128 v[36:39], v10 offset:42240
	ds_read_b128 v[32:35], v10 offset:41984
	ds_read_b128 v[44:47], v10 offset:42752
	ds_read_b128 v[40:43], v10 offset:42496
	s_waitcnt lgkmcnt(4)
	v_fma_mix_f32 v12, v6, v20, v180 op_sel_hi:[0,1,0]
	v_fma_mix_f32 v12, v7, v20, v12 op_sel:[0,1,0] op_sel_hi:[0,1,0]
	v_fma_mix_f32 v12, v8, v21, v12 op_sel_hi:[0,1,0]
	v_fma_mix_f32 v12, v9, v21, v12 op_sel:[0,1,0] op_sel_hi:[0,1,0]
	v_pk_mul_f32 v[48:49], v[6:7], v[16:17]
	v_pk_mul_f32 v[50:51], v[8:9], v[18:19]
	v_add_f32_dpp v12, v12, v12 row_ror:1 row_mask:0xf bank_mask:0xf bound_ctrl:1
	v_pk_fma_f32 v[48:49], v[28:29], v[66:67], v[48:49] op_sel_hi:[1,0,1]
	v_pk_fma_f32 v[50:51], v[30:31], v[66:67], v[50:51] op_sel_hi:[1,0,1]
	v_add_f32_dpp v12, v12, v12 row_ror:2 row_mask:0xf bank_mask:0xf bound_ctrl:1
	v_fma_mix_f32 v82, v6, v112, v180 op_sel_hi:[0,1,0]
	v_fma_mix_f32 v82, v7, v112, v82 op_sel:[0,1,0] op_sel_hi:[0,1,0]
	v_add_f32_dpp v12, v12, v12 row_ror:4 row_mask:0xf bank_mask:0xf bound_ctrl:1
	v_fma_mix_f32 v82, v8, v113, v82 op_sel_hi:[0,1,0]
	v_fma_mix_f32 v82, v9, v113, v82 op_sel:[0,1,0] op_sel_hi:[0,1,0]
	v_add_f32_dpp v12, v12, v12 row_ror:8 row_mask:0xf bank_mask:0xf bound_ctrl:1
	v_pk_fma_f32 v[6:7], v[24:25], v[12:13], v[48:49] op_sel_hi:[1,0,1] neg_lo:[1,0,0] neg_hi:[1,0,0]
	v_pk_fma_f32 v[8:9], v[26:27], v[12:13], v[50:51] op_sel_hi:[1,0,1] neg_lo:[1,0,0] neg_hi:[1,0,0]
	ds_read_b128 v[88:91], v10 offset:43264
	ds_read_b128 v[84:87], v10 offset:43008
	ds_read_b128 v[96:99], v10 offset:43776
	ds_read_b128 v[92:95], v10 offset:43520
	s_waitcnt lgkmcnt(4)
	v_fma_mix_f32 v12, v6, v36, v180 op_sel_hi:[0,1,0]
	v_fma_mix_f32 v12, v7, v36, v12 op_sel:[0,1,0] op_sel_hi:[0,1,0]
	v_fma_mix_f32 v12, v8, v37, v12 op_sel_hi:[0,1,0]
	v_fma_mix_f32 v12, v9, v37, v12 op_sel:[0,1,0] op_sel_hi:[0,1,0]
	v_pk_mul_f32 v[48:49], v[6:7], v[32:33]
	v_pk_mul_f32 v[50:51], v[8:9], v[34:35]
	v_add_f32_dpp v12, v12, v12 row_ror:1 row_mask:0xf bank_mask:0xf bound_ctrl:1
	v_pk_fma_f32 v[48:49], v[44:45], v[66:67], v[48:49] op_sel:[0,1,0]
	v_pk_fma_f32 v[50:51], v[46:47], v[66:67], v[50:51] op_sel:[0,1,0]
	v_add_f32_dpp v12, v12, v12 row_ror:2 row_mask:0xf bank_mask:0xf bound_ctrl:1
	v_fma_mix_f32 v83, v6, v22, v180 op_sel_hi:[0,1,0]
	v_fma_mix_f32 v83, v7, v22, v83 op_sel:[0,1,0] op_sel_hi:[0,1,0]
	v_add_f32_dpp v12, v12, v12 row_ror:4 row_mask:0xf bank_mask:0xf bound_ctrl:1
	v_fma_mix_f32 v83, v8, v23, v83 op_sel_hi:[0,1,0]
	v_fma_mix_f32 v83, v9, v23, v83 op_sel:[0,1,0] op_sel_hi:[0,1,0]
	v_add_f32_dpp v12, v12, v12 row_ror:8 row_mask:0xf bank_mask:0xf bound_ctrl:1
	v_pk_fma_f32 v[6:7], v[40:41], v[12:13], v[48:49] op_sel_hi:[1,0,1] neg_lo:[1,0,0] neg_hi:[1,0,0]
	v_pk_fma_f32 v[8:9], v[42:43], v[12:13], v[50:51] op_sel_hi:[1,0,1] neg_lo:[1,0,0] neg_hi:[1,0,0]
	ds_read_b128 v[110:113], v10 offset:44288
	ds_read_b128 v[106:109], v10 offset:44032
	ds_read_b128 v[118:121], v10 offset:44800
	ds_read_b128 v[114:117], v10 offset:44544
	ds_read_b128 v[70:73], v11 offset:2816
	s_waitcnt lgkmcnt(5)
	v_fma_mix_f32 v12, v6, v88, v180 op_sel_hi:[0,1,0]
	v_fma_mix_f32 v12, v7, v88, v12 op_sel:[0,1,0] op_sel_hi:[0,1,0]
	v_fma_mix_f32 v12, v8, v89, v12 op_sel_hi:[0,1,0]
	v_fma_mix_f32 v12, v9, v89, v12 op_sel:[0,1,0] op_sel_hi:[0,1,0]
	v_pk_mul_f32 v[48:49], v[6:7], v[84:85]
	v_pk_mul_f32 v[50:51], v[8:9], v[86:87]
	v_add_f32_dpp v12, v12, v12 row_ror:1 row_mask:0xf bank_mask:0xf bound_ctrl:1
	v_pk_fma_f32 v[48:49], v[96:97], v[68:69], v[48:49] op_sel_hi:[1,0,1]
	v_pk_fma_f32 v[50:51], v[98:99], v[68:69], v[50:51] op_sel_hi:[1,0,1]
	v_add_f32_dpp v12, v12, v12 row_ror:2 row_mask:0xf bank_mask:0xf bound_ctrl:1
	v_fma_mix_f32 v100, v6, v38, v180 op_sel_hi:[0,1,0]
	v_fma_mix_f32 v100, v7, v38, v100 op_sel:[0,1,0] op_sel_hi:[0,1,0]
	v_add_f32_dpp v12, v12, v12 row_ror:4 row_mask:0xf bank_mask:0xf bound_ctrl:1
	v_fma_mix_f32 v100, v8, v39, v100 op_sel_hi:[0,1,0]
	v_fma_mix_f32 v100, v9, v39, v100 op_sel:[0,1,0] op_sel_hi:[0,1,0]
	v_add_f32_dpp v12, v12, v12 row_ror:8 row_mask:0xf bank_mask:0xf bound_ctrl:1
	v_pk_fma_f32 v[6:7], v[92:93], v[12:13], v[48:49] op_sel_hi:[1,0,1] neg_lo:[1,0,0] neg_hi:[1,0,0]
	v_pk_fma_f32 v[8:9], v[94:95], v[12:13], v[50:51] op_sel_hi:[1,0,1] neg_lo:[1,0,0] neg_hi:[1,0,0]
	ds_read_b128 v[20:23], v10 offset:45312
	ds_read_b128 v[16:19], v10 offset:45056
	ds_read_b128 v[28:31], v10 offset:45824
	ds_read_b128 v[24:27], v10 offset:45568
	s_waitcnt lgkmcnt(5)
	v_fma_mix_f32 v12, v6, v110, v180 op_sel_hi:[0,1,0]
	v_fma_mix_f32 v12, v7, v110, v12 op_sel:[0,1,0] op_sel_hi:[0,1,0]
	v_fma_mix_f32 v12, v8, v111, v12 op_sel_hi:[0,1,0]
	v_fma_mix_f32 v12, v9, v111, v12 op_sel:[0,1,0] op_sel_hi:[0,1,0]
	v_pk_mul_f32 v[48:49], v[6:7], v[106:107]
	v_pk_mul_f32 v[50:51], v[8:9], v[108:109]
	v_add_f32_dpp v12, v12, v12 row_ror:1 row_mask:0xf bank_mask:0xf bound_ctrl:1
	v_pk_fma_f32 v[48:49], v[118:119], v[68:69], v[48:49] op_sel:[0,1,0]
	v_pk_fma_f32 v[50:51], v[120:121], v[68:69], v[50:51] op_sel:[0,1,0]
	v_add_f32_dpp v12, v12, v12 row_ror:2 row_mask:0xf bank_mask:0xf bound_ctrl:1
	v_fma_mix_f32 v101, v6, v90, v180 op_sel_hi:[0,1,0]
	v_fma_mix_f32 v101, v7, v90, v101 op_sel:[0,1,0] op_sel_hi:[0,1,0]
	v_add_f32_dpp v12, v12, v12 row_ror:4 row_mask:0xf bank_mask:0xf bound_ctrl:1
	v_fma_mix_f32 v101, v8, v91, v101 op_sel_hi:[0,1,0]
	v_fma_mix_f32 v101, v9, v91, v101 op_sel:[0,1,0] op_sel_hi:[0,1,0]
	v_add_f32_dpp v12, v12, v12 row_ror:8 row_mask:0xf bank_mask:0xf bound_ctrl:1
	v_pk_fma_f32 v[6:7], v[114:115], v[12:13], v[48:49] op_sel_hi:[1,0,1] neg_lo:[1,0,0] neg_hi:[1,0,0]
	v_pk_fma_f32 v[8:9], v[116:117], v[12:13], v[50:51] op_sel_hi:[1,0,1] neg_lo:[1,0,0] neg_hi:[1,0,0]
	ds_read_b128 v[36:39], v10 offset:46336
	ds_read_b128 v[32:35], v10 offset:46080
	ds_read_b128 v[44:47], v10 offset:46848
	ds_read_b128 v[40:43], v10 offset:46592
	s_waitcnt lgkmcnt(4)
	v_fma_mix_f32 v12, v6, v20, v180 op_sel_hi:[0,1,0]
	v_fma_mix_f32 v12, v7, v20, v12 op_sel:[0,1,0] op_sel_hi:[0,1,0]
	v_fma_mix_f32 v12, v8, v21, v12 op_sel_hi:[0,1,0]
	v_fma_mix_f32 v12, v9, v21, v12 op_sel:[0,1,0] op_sel_hi:[0,1,0]
	v_pk_mul_f32 v[48:49], v[6:7], v[16:17]
	v_pk_mul_f32 v[50:51], v[8:9], v[18:19]
	v_add_f32_dpp v12, v12, v12 row_ror:1 row_mask:0xf bank_mask:0xf bound_ctrl:1
	v_pk_fma_f32 v[48:49], v[28:29], v[70:71], v[48:49] op_sel_hi:[1,0,1]
	v_pk_fma_f32 v[50:51], v[30:31], v[70:71], v[50:51] op_sel_hi:[1,0,1]
	v_add_f32_dpp v12, v12, v12 row_ror:2 row_mask:0xf bank_mask:0xf bound_ctrl:1
	v_fma_mix_f32 v102, v6, v112, v180 op_sel_hi:[0,1,0]
	v_fma_mix_f32 v102, v7, v112, v102 op_sel:[0,1,0] op_sel_hi:[0,1,0]
	v_add_f32_dpp v12, v12, v12 row_ror:4 row_mask:0xf bank_mask:0xf bound_ctrl:1
	v_fma_mix_f32 v102, v8, v113, v102 op_sel_hi:[0,1,0]
	v_fma_mix_f32 v102, v9, v113, v102 op_sel:[0,1,0] op_sel_hi:[0,1,0]
	v_add_f32_dpp v12, v12, v12 row_ror:8 row_mask:0xf bank_mask:0xf bound_ctrl:1
	v_pk_fma_f32 v[6:7], v[24:25], v[12:13], v[48:49] op_sel_hi:[1,0,1] neg_lo:[1,0,0] neg_hi:[1,0,0]
	v_pk_fma_f32 v[8:9], v[26:27], v[12:13], v[50:51] op_sel_hi:[1,0,1] neg_lo:[1,0,0] neg_hi:[1,0,0]
	ds_read_b128 v[88:91], v10 offset:47360
	ds_read_b128 v[84:87], v10 offset:47104
	ds_read_b128 v[96:99], v10 offset:47872
	ds_read_b128 v[92:95], v10 offset:47616
	s_waitcnt lgkmcnt(4)
	v_fma_mix_f32 v12, v6, v36, v180 op_sel_hi:[0,1,0]
	v_fma_mix_f32 v12, v7, v36, v12 op_sel:[0,1,0] op_sel_hi:[0,1,0]
	v_fma_mix_f32 v12, v8, v37, v12 op_sel_hi:[0,1,0]
	v_fma_mix_f32 v12, v9, v37, v12 op_sel:[0,1,0] op_sel_hi:[0,1,0]
	v_pk_mul_f32 v[48:49], v[6:7], v[32:33]
	v_pk_mul_f32 v[50:51], v[8:9], v[34:35]
	v_add_f32_dpp v12, v12, v12 row_ror:1 row_mask:0xf bank_mask:0xf bound_ctrl:1
	v_pk_fma_f32 v[48:49], v[44:45], v[70:71], v[48:49] op_sel:[0,1,0]
	v_pk_fma_f32 v[50:51], v[46:47], v[70:71], v[50:51] op_sel:[0,1,0]
	v_add_f32_dpp v12, v12, v12 row_ror:2 row_mask:0xf bank_mask:0xf bound_ctrl:1
	v_fma_mix_f32 v103, v6, v22, v180 op_sel_hi:[0,1,0]
	v_fma_mix_f32 v103, v7, v22, v103 op_sel:[0,1,0] op_sel_hi:[0,1,0]
	v_add_f32_dpp v12, v12, v12 row_ror:4 row_mask:0xf bank_mask:0xf bound_ctrl:1
	v_fma_mix_f32 v103, v8, v23, v103 op_sel_hi:[0,1,0]
	v_fma_mix_f32 v103, v9, v23, v103 op_sel:[0,1,0] op_sel_hi:[0,1,0]
	v_add_f32_dpp v12, v12, v12 row_ror:8 row_mask:0xf bank_mask:0xf bound_ctrl:1
	v_pk_fma_f32 v[6:7], v[40:41], v[12:13], v[48:49] op_sel_hi:[1,0,1] neg_lo:[1,0,0] neg_hi:[1,0,0]
	v_pk_fma_f32 v[8:9], v[42:43], v[12:13], v[50:51] op_sel_hi:[1,0,1] neg_lo:[1,0,0] neg_hi:[1,0,0]
	ds_read_b128 v[110:113], v10 offset:48384
	ds_read_b128 v[106:109], v10 offset:48128
	ds_read_b128 v[118:121], v10 offset:48896
	ds_read_b128 v[114:117], v10 offset:48640
	ds_read_b128 v[66:69], v11 offset:3072
	s_waitcnt lgkmcnt(5)
	v_fma_mix_f32 v12, v6, v88, v180 op_sel_hi:[0,1,0]
	v_fma_mix_f32 v12, v7, v88, v12 op_sel:[0,1,0] op_sel_hi:[0,1,0]
	v_fma_mix_f32 v12, v8, v89, v12 op_sel_hi:[0,1,0]
	v_fma_mix_f32 v12, v9, v89, v12 op_sel:[0,1,0] op_sel_hi:[0,1,0]
	v_pk_mul_f32 v[48:49], v[6:7], v[84:85]
	v_pk_mul_f32 v[50:51], v[8:9], v[86:87]
	v_add_f32_dpp v12, v12, v12 row_ror:1 row_mask:0xf bank_mask:0xf bound_ctrl:1
	v_pk_fma_f32 v[48:49], v[96:97], v[72:73], v[48:49] op_sel_hi:[1,0,1]
	v_pk_fma_f32 v[50:51], v[98:99], v[72:73], v[50:51] op_sel_hi:[1,0,1]
	v_add_f32_dpp v12, v12, v12 row_ror:2 row_mask:0xf bank_mask:0xf bound_ctrl:1
	v_fma_mix_f32 v104, v6, v38, v180 op_sel_hi:[0,1,0]
	v_fma_mix_f32 v104, v7, v38, v104 op_sel:[0,1,0] op_sel_hi:[0,1,0]
	v_add_f32_dpp v12, v12, v12 row_ror:4 row_mask:0xf bank_mask:0xf bound_ctrl:1
	v_fma_mix_f32 v104, v8, v39, v104 op_sel_hi:[0,1,0]
	v_fma_mix_f32 v104, v9, v39, v104 op_sel:[0,1,0] op_sel_hi:[0,1,0]
	v_add_f32_dpp v12, v12, v12 row_ror:8 row_mask:0xf bank_mask:0xf bound_ctrl:1
	v_pk_fma_f32 v[6:7], v[92:93], v[12:13], v[48:49] op_sel_hi:[1,0,1] neg_lo:[1,0,0] neg_hi:[1,0,0]
	v_pk_fma_f32 v[8:9], v[94:95], v[12:13], v[50:51] op_sel_hi:[1,0,1] neg_lo:[1,0,0] neg_hi:[1,0,0]
	ds_read_b128 v[20:23], v10 offset:49408
	ds_read_b128 v[16:19], v10 offset:49152
	ds_read_b128 v[28:31], v10 offset:49920
	ds_read_b128 v[24:27], v10 offset:49664
	s_waitcnt lgkmcnt(5)
	v_fma_mix_f32 v12, v6, v110, v180 op_sel_hi:[0,1,0]
	v_fma_mix_f32 v12, v7, v110, v12 op_sel:[0,1,0] op_sel_hi:[0,1,0]
	v_fma_mix_f32 v12, v8, v111, v12 op_sel_hi:[0,1,0]
	v_fma_mix_f32 v12, v9, v111, v12 op_sel:[0,1,0] op_sel_hi:[0,1,0]
	v_pk_mul_f32 v[48:49], v[6:7], v[106:107]
	v_pk_mul_f32 v[50:51], v[8:9], v[108:109]
	v_add_f32_dpp v12, v12, v12 row_ror:1 row_mask:0xf bank_mask:0xf bound_ctrl:1
	v_pk_fma_f32 v[48:49], v[118:119], v[72:73], v[48:49] op_sel:[0,1,0]
	v_pk_fma_f32 v[50:51], v[120:121], v[72:73], v[50:51] op_sel:[0,1,0]
	v_add_f32_dpp v12, v12, v12 row_ror:2 row_mask:0xf bank_mask:0xf bound_ctrl:1
	v_fma_mix_f32 v105, v6, v90, v180 op_sel_hi:[0,1,0]
	v_fma_mix_f32 v105, v7, v90, v105 op_sel:[0,1,0] op_sel_hi:[0,1,0]
	v_add_f32_dpp v12, v12, v12 row_ror:4 row_mask:0xf bank_mask:0xf bound_ctrl:1
	v_fma_mix_f32 v105, v8, v91, v105 op_sel_hi:[0,1,0]
	v_fma_mix_f32 v105, v9, v91, v105 op_sel:[0,1,0] op_sel_hi:[0,1,0]
	v_add_f32_dpp v12, v12, v12 row_ror:8 row_mask:0xf bank_mask:0xf bound_ctrl:1
	v_pk_fma_f32 v[6:7], v[114:115], v[12:13], v[48:49] op_sel_hi:[1,0,1] neg_lo:[1,0,0] neg_hi:[1,0,0]
	v_pk_fma_f32 v[8:9], v[116:117], v[12:13], v[50:51] op_sel_hi:[1,0,1] neg_lo:[1,0,0] neg_hi:[1,0,0]
	ds_read_b128 v[36:39], v10 offset:50432
	ds_read_b128 v[32:35], v10 offset:50176
	ds_read_b128 v[44:47], v10 offset:50944
	ds_read_b128 v[40:43], v10 offset:50688
	s_waitcnt lgkmcnt(4)
	v_fma_mix_f32 v12, v6, v20, v180 op_sel_hi:[0,1,0]
	v_fma_mix_f32 v12, v7, v20, v12 op_sel:[0,1,0] op_sel_hi:[0,1,0]
	v_fma_mix_f32 v12, v8, v21, v12 op_sel_hi:[0,1,0]
	v_fma_mix_f32 v12, v9, v21, v12 op_sel:[0,1,0] op_sel_hi:[0,1,0]
	v_pk_mul_f32 v[48:49], v[6:7], v[16:17]
	v_pk_mul_f32 v[50:51], v[8:9], v[18:19]
	v_add_f32_dpp v12, v12, v12 row_ror:1 row_mask:0xf bank_mask:0xf bound_ctrl:1
	v_pk_fma_f32 v[48:49], v[28:29], v[66:67], v[48:49] op_sel_hi:[1,0,1]
	v_pk_fma_f32 v[50:51], v[30:31], v[66:67], v[50:51] op_sel_hi:[1,0,1]
	v_add_f32_dpp v12, v12, v12 row_ror:2 row_mask:0xf bank_mask:0xf bound_ctrl:1
	v_fma_mix_f32 v61, v6, v112, v180 op_sel_hi:[0,1,0]
	v_fma_mix_f32 v61, v7, v112, v61 op_sel:[0,1,0] op_sel_hi:[0,1,0]
	v_add_f32_dpp v12, v12, v12 row_ror:4 row_mask:0xf bank_mask:0xf bound_ctrl:1
	v_fma_mix_f32 v61, v8, v113, v61 op_sel_hi:[0,1,0]
	v_fma_mix_f32 v61, v9, v113, v61 op_sel:[0,1,0] op_sel_hi:[0,1,0]
	v_add_f32_dpp v12, v12, v12 row_ror:8 row_mask:0xf bank_mask:0xf bound_ctrl:1
	v_pk_fma_f32 v[6:7], v[24:25], v[12:13], v[48:49] op_sel_hi:[1,0,1] neg_lo:[1,0,0] neg_hi:[1,0,0]
	v_pk_fma_f32 v[8:9], v[26:27], v[12:13], v[50:51] op_sel_hi:[1,0,1] neg_lo:[1,0,0] neg_hi:[1,0,0]
	ds_read_b128 v[88:91], v10 offset:51456
	ds_read_b128 v[84:87], v10 offset:51200
	ds_read_b128 v[96:99], v10 offset:51968
	ds_read_b128 v[92:95], v10 offset:51712
	v_add_f32_dpp v83, v83, v83 row_ror:8 row_mask:0xf bank_mask:0xc
	v_add_f32_dpp v83, v52, v52 row_ror:8 row_mask:0xf bank_mask:0x3
	v_add_f32_dpp v100, v100, v100 row_ror:8 row_mask:0xf bank_mask:0xc
	v_add_f32_dpp v100, v53, v53 row_ror:8 row_mask:0xf bank_mask:0x3
	v_add_f32_dpp v101, v101, v101 row_ror:8 row_mask:0xf bank_mask:0xc
	v_add_f32_dpp v101, v54, v54 row_ror:8 row_mask:0xf bank_mask:0x3
	v_add_f32_dpp v102, v102, v102 row_ror:8 row_mask:0xf bank_mask:0xc
	v_add_f32_dpp v102, v55, v55 row_ror:8 row_mask:0xf bank_mask:0x3
	v_add_f32_dpp v103, v103, v103 row_ror:8 row_mask:0xf bank_mask:0xc
	v_add_f32_dpp v103, v56, v56 row_ror:8 row_mask:0xf bank_mask:0x3
	v_add_f32_dpp v104, v104, v104 row_ror:8 row_mask:0xf bank_mask:0xc
	v_add_f32_dpp v104, v57, v57 row_ror:8 row_mask:0xf bank_mask:0x3
	v_add_f32_dpp v105, v105, v105 row_ror:8 row_mask:0xf bank_mask:0xc
	v_add_f32_dpp v105, v81, v81 row_ror:8 row_mask:0xf bank_mask:0x3
	v_add_f32_dpp v61, v61, v61 row_ror:8 row_mask:0xf bank_mask:0xc
	v_add_f32_dpp v61, v82, v82 row_ror:8 row_mask:0xf bank_mask:0x3
	v_add_f32_dpp v103, v103, v103 row_ror:4 row_mask:0xf bank_mask:0xa
	v_add_f32_dpp v103, v83, v83 row_ror:12 row_mask:0xf bank_mask:0x5
	v_add_f32_dpp v104, v104, v104 row_ror:4 row_mask:0xf bank_mask:0xa
	v_add_f32_dpp v104, v100, v100 row_ror:12 row_mask:0xf bank_mask:0x5
	v_add_f32_dpp v105, v105, v105 row_ror:4 row_mask:0xf bank_mask:0xa
	v_add_f32_dpp v105, v101, v101 row_ror:12 row_mask:0xf bank_mask:0x5
	v_add_f32_dpp v61, v61, v61 row_ror:4 row_mask:0xf bank_mask:0xa
	v_add_f32_dpp v61, v102, v102 row_ror:12 row_mask:0xf bank_mask:0x5
	v_cndmask_b32_e64 v62, v105, v103, s[38:39]
	v_cndmask_b32_e64 v63, v103, v105, s[38:39]
	v_cndmask_b32_e64 v64, v61, v104, s[38:39]
	v_cndmask_b32_e64 v65, v104, v61, s[38:39]
	v_add_f32_dpp v62, v63, v62 quad_perm:[2,3,0,1] row_mask:0xf bank_mask:0xf bound_ctrl:1
	s_nop 0
	v_add_f32_dpp v63, v65, v64 quad_perm:[2,3,0,1] row_mask:0xf bank_mask:0xf bound_ctrl:1
	v_cndmask_b32_e64 v65, v63, v62, s[40:41]
	v_cndmask_b32_e64 v62, v62, v63, s[40:41]
	s_nop 1
	v_add_f32_dpp v62, v62, v65 quad_perm:[1,0,3,2] row_mask:0xf bank_mask:0xf bound_ctrl:1
	v_cvt_pk_bf16_f32 v62, v62, v62
	global_store_short v[2:3], v62, off
	v_lshl_add_u64 v[2:3], v[2:3], 0, s[84:85]
	s_waitcnt lgkmcnt(4)
	v_fma_mix_f32 v12, v6, v36, v180 op_sel_hi:[0,1,0]
	v_fma_mix_f32 v12, v7, v36, v12 op_sel:[0,1,0] op_sel_hi:[0,1,0]
	v_fma_mix_f32 v12, v8, v37, v12 op_sel_hi:[0,1,0]
	v_fma_mix_f32 v12, v9, v37, v12 op_sel:[0,1,0] op_sel_hi:[0,1,0]
	v_pk_mul_f32 v[48:49], v[6:7], v[32:33]
	v_pk_mul_f32 v[50:51], v[8:9], v[34:35]
	v_add_f32_dpp v12, v12, v12 row_ror:1 row_mask:0xf bank_mask:0xf bound_ctrl:1
	v_pk_fma_f32 v[48:49], v[44:45], v[66:67], v[48:49] op_sel:[0,1,0]
	v_pk_fma_f32 v[50:51], v[46:47], v[66:67], v[50:51] op_sel:[0,1,0]
	v_add_f32_dpp v12, v12, v12 row_ror:2 row_mask:0xf bank_mask:0xf bound_ctrl:1
	v_fma_mix_f32 v52, v6, v22, v180 op_sel_hi:[0,1,0]
	v_fma_mix_f32 v52, v7, v22, v52 op_sel:[0,1,0] op_sel_hi:[0,1,0]
	v_add_f32_dpp v12, v12, v12 row_ror:4 row_mask:0xf bank_mask:0xf bound_ctrl:1
	v_fma_mix_f32 v52, v8, v23, v52 op_sel_hi:[0,1,0]
	v_fma_mix_f32 v52, v9, v23, v52 op_sel:[0,1,0] op_sel_hi:[0,1,0]
	v_add_f32_dpp v12, v12, v12 row_ror:8 row_mask:0xf bank_mask:0xf bound_ctrl:1
	v_pk_fma_f32 v[6:7], v[40:41], v[12:13], v[48:49] op_sel_hi:[1,0,1] neg_lo:[1,0,0] neg_hi:[1,0,0]
	v_pk_fma_f32 v[8:9], v[42:43], v[12:13], v[50:51] op_sel_hi:[1,0,1] neg_lo:[1,0,0] neg_hi:[1,0,0]
	ds_read_b128 v[110:113], v10 offset:52480
	ds_read_b128 v[106:109], v10 offset:52224
	ds_read_b128 v[118:121], v10 offset:52992
	ds_read_b128 v[114:117], v10 offset:52736
	ds_read_b128 v[70:73], v11 offset:3328
	s_waitcnt lgkmcnt(5)
	v_fma_mix_f32 v12, v6, v88, v180 op_sel_hi:[0,1,0]
	v_fma_mix_f32 v12, v7, v88, v12 op_sel:[0,1,0] op_sel_hi:[0,1,0]
	v_fma_mix_f32 v12, v8, v89, v12 op_sel_hi:[0,1,0]
	v_fma_mix_f32 v12, v9, v89, v12 op_sel:[0,1,0] op_sel_hi:[0,1,0]
	v_pk_mul_f32 v[48:49], v[6:7], v[84:85]
	v_pk_mul_f32 v[50:51], v[8:9], v[86:87]
	v_add_f32_dpp v12, v12, v12 row_ror:1 row_mask:0xf bank_mask:0xf bound_ctrl:1
	v_pk_fma_f32 v[48:49], v[96:97], v[68:69], v[48:49] op_sel_hi:[1,0,1]
	v_pk_fma_f32 v[50:51], v[98:99], v[68:69], v[50:51] op_sel_hi:[1,0,1]
	v_add_f32_dpp v12, v12, v12 row_ror:2 row_mask:0xf bank_mask:0xf bound_ctrl:1
	v_fma_mix_f32 v53, v6, v38, v180 op_sel_hi:[0,1,0]
	v_fma_mix_f32 v53, v7, v38, v53 op_sel:[0,1,0] op_sel_hi:[0,1,0]
	v_add_f32_dpp v12, v12, v12 row_ror:4 row_mask:0xf bank_mask:0xf bound_ctrl:1
	v_fma_mix_f32 v53, v8, v39, v53 op_sel_hi:[0,1,0]
	v_fma_mix_f32 v53, v9, v39, v53 op_sel:[0,1,0] op_sel_hi:[0,1,0]
	v_add_f32_dpp v12, v12, v12 row_ror:8 row_mask:0xf bank_mask:0xf bound_ctrl:1
	v_pk_fma_f32 v[6:7], v[92:93], v[12:13], v[48:49] op_sel_hi:[1,0,1] neg_lo:[1,0,0] neg_hi:[1,0,0]
	v_pk_fma_f32 v[8:9], v[94:95], v[12:13], v[50:51] op_sel_hi:[1,0,1] neg_lo:[1,0,0] neg_hi:[1,0,0]
	ds_read_b128 v[20:23], v10 offset:53504
	ds_read_b128 v[16:19], v10 offset:53248
	ds_read_b128 v[28:31], v10 offset:54016
	ds_read_b128 v[24:27], v10 offset:53760
	s_waitcnt lgkmcnt(5)
	v_fma_mix_f32 v12, v6, v110, v180 op_sel_hi:[0,1,0]
	v_fma_mix_f32 v12, v7, v110, v12 op_sel:[0,1,0] op_sel_hi:[0,1,0]
	v_fma_mix_f32 v12, v8, v111, v12 op_sel_hi:[0,1,0]
	v_fma_mix_f32 v12, v9, v111, v12 op_sel:[0,1,0] op_sel_hi:[0,1,0]
	v_pk_mul_f32 v[48:49], v[6:7], v[106:107]
	v_pk_mul_f32 v[50:51], v[8:9], v[108:109]
	v_add_f32_dpp v12, v12, v12 row_ror:1 row_mask:0xf bank_mask:0xf bound_ctrl:1
	v_pk_fma_f32 v[48:49], v[118:119], v[68:69], v[48:49] op_sel:[0,1,0]
	v_pk_fma_f32 v[50:51], v[120:121], v[68:69], v[50:51] op_sel:[0,1,0]
	v_add_f32_dpp v12, v12, v12 row_ror:2 row_mask:0xf bank_mask:0xf bound_ctrl:1
	v_fma_mix_f32 v54, v6, v90, v180 op_sel_hi:[0,1,0]
	v_fma_mix_f32 v54, v7, v90, v54 op_sel:[0,1,0] op_sel_hi:[0,1,0]
	v_add_f32_dpp v12, v12, v12 row_ror:4 row_mask:0xf bank_mask:0xf bound_ctrl:1
	v_fma_mix_f32 v54, v8, v91, v54 op_sel_hi:[0,1,0]
	v_fma_mix_f32 v54, v9, v91, v54 op_sel:[0,1,0] op_sel_hi:[0,1,0]
	v_add_f32_dpp v12, v12, v12 row_ror:8 row_mask:0xf bank_mask:0xf bound_ctrl:1
	v_pk_fma_f32 v[6:7], v[114:115], v[12:13], v[48:49] op_sel_hi:[1,0,1] neg_lo:[1,0,0] neg_hi:[1,0,0]
	v_pk_fma_f32 v[8:9], v[116:117], v[12:13], v[50:51] op_sel_hi:[1,0,1] neg_lo:[1,0,0] neg_hi:[1,0,0]
	ds_read_b128 v[36:39], v10 offset:54528
	ds_read_b128 v[32:35], v10 offset:54272
	ds_read_b128 v[44:47], v10 offset:55040
	ds_read_b128 v[40:43], v10 offset:54784
	s_waitcnt lgkmcnt(4)
	v_fma_mix_f32 v12, v6, v20, v180 op_sel_hi:[0,1,0]
	v_fma_mix_f32 v12, v7, v20, v12 op_sel:[0,1,0] op_sel_hi:[0,1,0]
	v_fma_mix_f32 v12, v8, v21, v12 op_sel_hi:[0,1,0]
	v_fma_mix_f32 v12, v9, v21, v12 op_sel:[0,1,0] op_sel_hi:[0,1,0]
	v_pk_mul_f32 v[48:49], v[6:7], v[16:17]
	v_pk_mul_f32 v[50:51], v[8:9], v[18:19]
	v_add_f32_dpp v12, v12, v12 row_ror:1 row_mask:0xf bank_mask:0xf bound_ctrl:1
	v_pk_fma_f32 v[48:49], v[28:29], v[70:71], v[48:49] op_sel_hi:[1,0,1]
	v_pk_fma_f32 v[50:51], v[30:31], v[70:71], v[50:51] op_sel_hi:[1,0,1]
	v_add_f32_dpp v12, v12, v12 row_ror:2 row_mask:0xf bank_mask:0xf bound_ctrl:1
	v_fma_mix_f32 v55, v6, v112, v180 op_sel_hi:[0,1,0]
	v_fma_mix_f32 v55, v7, v112, v55 op_sel:[0,1,0] op_sel_hi:[0,1,0]
	v_add_f32_dpp v12, v12, v12 row_ror:4 row_mask:0xf bank_mask:0xf bound_ctrl:1
	v_fma_mix_f32 v55, v8, v113, v55 op_sel_hi:[0,1,0]
	v_fma_mix_f32 v55, v9, v113, v55 op_sel:[0,1,0] op_sel_hi:[0,1,0]
	v_add_f32_dpp v12, v12, v12 row_ror:8 row_mask:0xf bank_mask:0xf bound_ctrl:1
	v_pk_fma_f32 v[6:7], v[24:25], v[12:13], v[48:49] op_sel_hi:[1,0,1] neg_lo:[1,0,0] neg_hi:[1,0,0]
	v_pk_fma_f32 v[8:9], v[26:27], v[12:13], v[50:51] op_sel_hi:[1,0,1] neg_lo:[1,0,0] neg_hi:[1,0,0]
	ds_read_b128 v[88:91], v10 offset:55552
	ds_read_b128 v[84:87], v10 offset:55296
	ds_read_b128 v[96:99], v10 offset:56064
	ds_read_b128 v[92:95], v10 offset:55808
	s_waitcnt lgkmcnt(4)
	v_fma_mix_f32 v12, v6, v36, v180 op_sel_hi:[0,1,0]
	v_fma_mix_f32 v12, v7, v36, v12 op_sel:[0,1,0] op_sel_hi:[0,1,0]
	v_fma_mix_f32 v12, v8, v37, v12 op_sel_hi:[0,1,0]
	v_fma_mix_f32 v12, v9, v37, v12 op_sel:[0,1,0] op_sel_hi:[0,1,0]
	v_pk_mul_f32 v[48:49], v[6:7], v[32:33]
	v_pk_mul_f32 v[50:51], v[8:9], v[34:35]
	v_add_f32_dpp v12, v12, v12 row_ror:1 row_mask:0xf bank_mask:0xf bound_ctrl:1
	v_pk_fma_f32 v[48:49], v[44:45], v[70:71], v[48:49] op_sel:[0,1,0]
	v_pk_fma_f32 v[50:51], v[46:47], v[70:71], v[50:51] op_sel:[0,1,0]
	v_add_f32_dpp v12, v12, v12 row_ror:2 row_mask:0xf bank_mask:0xf bound_ctrl:1
	v_fma_mix_f32 v56, v6, v22, v180 op_sel_hi:[0,1,0]
	v_fma_mix_f32 v56, v7, v22, v56 op_sel:[0,1,0] op_sel_hi:[0,1,0]
	v_add_f32_dpp v12, v12, v12 row_ror:4 row_mask:0xf bank_mask:0xf bound_ctrl:1
	v_fma_mix_f32 v56, v8, v23, v56 op_sel_hi:[0,1,0]
	v_fma_mix_f32 v56, v9, v23, v56 op_sel:[0,1,0] op_sel_hi:[0,1,0]
	v_add_f32_dpp v12, v12, v12 row_ror:8 row_mask:0xf bank_mask:0xf bound_ctrl:1
	v_pk_fma_f32 v[6:7], v[40:41], v[12:13], v[48:49] op_sel_hi:[1,0,1] neg_lo:[1,0,0] neg_hi:[1,0,0]
	v_pk_fma_f32 v[8:9], v[42:43], v[12:13], v[50:51] op_sel_hi:[1,0,1] neg_lo:[1,0,0] neg_hi:[1,0,0]
	ds_read_b128 v[110:113], v10 offset:56576
	ds_read_b128 v[106:109], v10 offset:56320
	ds_read_b128 v[118:121], v10 offset:57088
	ds_read_b128 v[114:117], v10 offset:56832
	ds_read_b128 v[66:69], v11 offset:3584
	s_waitcnt lgkmcnt(5)
	v_fma_mix_f32 v12, v6, v88, v180 op_sel_hi:[0,1,0]
	v_fma_mix_f32 v12, v7, v88, v12 op_sel:[0,1,0] op_sel_hi:[0,1,0]
	v_fma_mix_f32 v12, v8, v89, v12 op_sel_hi:[0,1,0]
	v_fma_mix_f32 v12, v9, v89, v12 op_sel:[0,1,0] op_sel_hi:[0,1,0]
	v_pk_mul_f32 v[48:49], v[6:7], v[84:85]
	v_pk_mul_f32 v[50:51], v[8:9], v[86:87]
	v_add_f32_dpp v12, v12, v12 row_ror:1 row_mask:0xf bank_mask:0xf bound_ctrl:1
	v_pk_fma_f32 v[48:49], v[96:97], v[72:73], v[48:49] op_sel_hi:[1,0,1]
	v_pk_fma_f32 v[50:51], v[98:99], v[72:73], v[50:51] op_sel_hi:[1,0,1]
	v_add_f32_dpp v12, v12, v12 row_ror:2 row_mask:0xf bank_mask:0xf bound_ctrl:1
	v_fma_mix_f32 v57, v6, v38, v180 op_sel_hi:[0,1,0]
	v_fma_mix_f32 v57, v7, v38, v57 op_sel:[0,1,0] op_sel_hi:[0,1,0]
	v_add_f32_dpp v12, v12, v12 row_ror:4 row_mask:0xf bank_mask:0xf bound_ctrl:1
	v_fma_mix_f32 v57, v8, v39, v57 op_sel_hi:[0,1,0]
	v_fma_mix_f32 v57, v9, v39, v57 op_sel:[0,1,0] op_sel_hi:[0,1,0]
	v_add_f32_dpp v12, v12, v12 row_ror:8 row_mask:0xf bank_mask:0xf bound_ctrl:1
	v_pk_fma_f32 v[6:7], v[92:93], v[12:13], v[48:49] op_sel_hi:[1,0,1] neg_lo:[1,0,0] neg_hi:[1,0,0]
	v_pk_fma_f32 v[8:9], v[94:95], v[12:13], v[50:51] op_sel_hi:[1,0,1] neg_lo:[1,0,0] neg_hi:[1,0,0]
	ds_read_b128 v[20:23], v10 offset:57600
	ds_read_b128 v[16:19], v10 offset:57344
	ds_read_b128 v[28:31], v10 offset:58112
	ds_read_b128 v[24:27], v10 offset:57856
	s_waitcnt lgkmcnt(5)
	v_fma_mix_f32 v12, v6, v110, v180 op_sel_hi:[0,1,0]
	v_fma_mix_f32 v12, v7, v110, v12 op_sel:[0,1,0] op_sel_hi:[0,1,0]
	v_fma_mix_f32 v12, v8, v111, v12 op_sel_hi:[0,1,0]
	v_fma_mix_f32 v12, v9, v111, v12 op_sel:[0,1,0] op_sel_hi:[0,1,0]
	v_pk_mul_f32 v[48:49], v[6:7], v[106:107]
	v_pk_mul_f32 v[50:51], v[8:9], v[108:109]
	v_add_f32_dpp v12, v12, v12 row_ror:1 row_mask:0xf bank_mask:0xf bound_ctrl:1
	v_pk_fma_f32 v[48:49], v[118:119], v[72:73], v[48:49] op_sel:[0,1,0]
	v_pk_fma_f32 v[50:51], v[120:121], v[72:73], v[50:51] op_sel:[0,1,0]
	v_add_f32_dpp v12, v12, v12 row_ror:2 row_mask:0xf bank_mask:0xf bound_ctrl:1
	v_fma_mix_f32 v81, v6, v90, v180 op_sel_hi:[0,1,0]
	v_fma_mix_f32 v81, v7, v90, v81 op_sel:[0,1,0] op_sel_hi:[0,1,0]
	v_add_f32_dpp v12, v12, v12 row_ror:4 row_mask:0xf bank_mask:0xf bound_ctrl:1
	v_fma_mix_f32 v81, v8, v91, v81 op_sel_hi:[0,1,0]
	v_fma_mix_f32 v81, v9, v91, v81 op_sel:[0,1,0] op_sel_hi:[0,1,0]
	v_add_f32_dpp v12, v12, v12 row_ror:8 row_mask:0xf bank_mask:0xf bound_ctrl:1
	v_pk_fma_f32 v[6:7], v[114:115], v[12:13], v[48:49] op_sel_hi:[1,0,1] neg_lo:[1,0,0] neg_hi:[1,0,0]
	v_pk_fma_f32 v[8:9], v[116:117], v[12:13], v[50:51] op_sel_hi:[1,0,1] neg_lo:[1,0,0] neg_hi:[1,0,0]
	ds_read_b128 v[36:39], v10 offset:58624
	ds_read_b128 v[32:35], v10 offset:58368
	ds_read_b128 v[44:47], v10 offset:59136
	ds_read_b128 v[40:43], v10 offset:58880
	s_waitcnt lgkmcnt(4)
	v_fma_mix_f32 v12, v6, v20, v180 op_sel_hi:[0,1,0]
	v_fma_mix_f32 v12, v7, v20, v12 op_sel:[0,1,0] op_sel_hi:[0,1,0]
	v_fma_mix_f32 v12, v8, v21, v12 op_sel_hi:[0,1,0]
	v_fma_mix_f32 v12, v9, v21, v12 op_sel:[0,1,0] op_sel_hi:[0,1,0]
	v_pk_mul_f32 v[48:49], v[6:7], v[16:17]
	v_pk_mul_f32 v[50:51], v[8:9], v[18:19]
	v_add_f32_dpp v12, v12, v12 row_ror:1 row_mask:0xf bank_mask:0xf bound_ctrl:1
	v_pk_fma_f32 v[48:49], v[28:29], v[66:67], v[48:49] op_sel_hi:[1,0,1]
	v_pk_fma_f32 v[50:51], v[30:31], v[66:67], v[50:51] op_sel_hi:[1,0,1]
	v_add_f32_dpp v12, v12, v12 row_ror:2 row_mask:0xf bank_mask:0xf bound_ctrl:1
	v_fma_mix_f32 v82, v6, v112, v180 op_sel_hi:[0,1,0]
	v_fma_mix_f32 v82, v7, v112, v82 op_sel:[0,1,0] op_sel_hi:[0,1,0]
	v_add_f32_dpp v12, v12, v12 row_ror:4 row_mask:0xf bank_mask:0xf bound_ctrl:1
	v_fma_mix_f32 v82, v8, v113, v82 op_sel_hi:[0,1,0]
	v_fma_mix_f32 v82, v9, v113, v82 op_sel:[0,1,0] op_sel_hi:[0,1,0]
	v_add_f32_dpp v12, v12, v12 row_ror:8 row_mask:0xf bank_mask:0xf bound_ctrl:1
	v_pk_fma_f32 v[6:7], v[24:25], v[12:13], v[48:49] op_sel_hi:[1,0,1] neg_lo:[1,0,0] neg_hi:[1,0,0]
	v_pk_fma_f32 v[8:9], v[26:27], v[12:13], v[50:51] op_sel_hi:[1,0,1] neg_lo:[1,0,0] neg_hi:[1,0,0]
	ds_read_b128 v[88:91], v10 offset:59648
	ds_read_b128 v[84:87], v10 offset:59392
	ds_read_b128 v[96:99], v10 offset:60160
	ds_read_b128 v[92:95], v10 offset:59904
	s_waitcnt lgkmcnt(4)
	v_fma_mix_f32 v12, v6, v36, v180 op_sel_hi:[0,1,0]
	v_fma_mix_f32 v12, v7, v36, v12 op_sel:[0,1,0] op_sel_hi:[0,1,0]
	v_fma_mix_f32 v12, v8, v37, v12 op_sel_hi:[0,1,0]
	v_fma_mix_f32 v12, v9, v37, v12 op_sel:[0,1,0] op_sel_hi:[0,1,0]
	v_pk_mul_f32 v[48:49], v[6:7], v[32:33]
	v_pk_mul_f32 v[50:51], v[8:9], v[34:35]
	v_add_f32_dpp v12, v12, v12 row_ror:1 row_mask:0xf bank_mask:0xf bound_ctrl:1
	v_pk_fma_f32 v[48:49], v[44:45], v[66:67], v[48:49] op_sel:[0,1,0]
	v_pk_fma_f32 v[50:51], v[46:47], v[66:67], v[50:51] op_sel:[0,1,0]
	v_add_f32_dpp v12, v12, v12 row_ror:2 row_mask:0xf bank_mask:0xf bound_ctrl:1
	v_fma_mix_f32 v83, v6, v22, v180 op_sel_hi:[0,1,0]
	v_fma_mix_f32 v83, v7, v22, v83 op_sel:[0,1,0] op_sel_hi:[0,1,0]
	v_add_f32_dpp v12, v12, v12 row_ror:4 row_mask:0xf bank_mask:0xf bound_ctrl:1
	v_fma_mix_f32 v83, v8, v23, v83 op_sel_hi:[0,1,0]
	v_fma_mix_f32 v83, v9, v23, v83 op_sel:[0,1,0] op_sel_hi:[0,1,0]
	v_add_f32_dpp v12, v12, v12 row_ror:8 row_mask:0xf bank_mask:0xf bound_ctrl:1
	v_pk_fma_f32 v[6:7], v[40:41], v[12:13], v[48:49] op_sel_hi:[1,0,1] neg_lo:[1,0,0] neg_hi:[1,0,0]
	v_pk_fma_f32 v[8:9], v[42:43], v[12:13], v[50:51] op_sel_hi:[1,0,1] neg_lo:[1,0,0] neg_hi:[1,0,0]
	ds_read_b128 v[110:113], v10 offset:60672
	ds_read_b128 v[106:109], v10 offset:60416
	ds_read_b128 v[118:121], v10 offset:61184
	ds_read_b128 v[114:117], v10 offset:60928
	ds_read_b128 v[70:73], v11 offset:3840
	s_waitcnt lgkmcnt(5)
	v_fma_mix_f32 v12, v6, v88, v180 op_sel_hi:[0,1,0]
	v_fma_mix_f32 v12, v7, v88, v12 op_sel:[0,1,0] op_sel_hi:[0,1,0]
	v_fma_mix_f32 v12, v8, v89, v12 op_sel_hi:[0,1,0]
	v_fma_mix_f32 v12, v9, v89, v12 op_sel:[0,1,0] op_sel_hi:[0,1,0]
	v_pk_mul_f32 v[48:49], v[6:7], v[84:85]
	v_pk_mul_f32 v[50:51], v[8:9], v[86:87]
	v_add_f32_dpp v12, v12, v12 row_ror:1 row_mask:0xf bank_mask:0xf bound_ctrl:1
	v_pk_fma_f32 v[48:49], v[96:97], v[68:69], v[48:49] op_sel_hi:[1,0,1]
	v_pk_fma_f32 v[50:51], v[98:99], v[68:69], v[50:51] op_sel_hi:[1,0,1]
	v_add_f32_dpp v12, v12, v12 row_ror:2 row_mask:0xf bank_mask:0xf bound_ctrl:1
	v_fma_mix_f32 v100, v6, v38, v180 op_sel_hi:[0,1,0]
	v_fma_mix_f32 v100, v7, v38, v100 op_sel:[0,1,0] op_sel_hi:[0,1,0]
	v_add_f32_dpp v12, v12, v12 row_ror:4 row_mask:0xf bank_mask:0xf bound_ctrl:1
	v_fma_mix_f32 v100, v8, v39, v100 op_sel_hi:[0,1,0]
	v_fma_mix_f32 v100, v9, v39, v100 op_sel:[0,1,0] op_sel_hi:[0,1,0]
	v_add_f32_dpp v12, v12, v12 row_ror:8 row_mask:0xf bank_mask:0xf bound_ctrl:1
	v_pk_fma_f32 v[6:7], v[92:93], v[12:13], v[48:49] op_sel_hi:[1,0,1] neg_lo:[1,0,0] neg_hi:[1,0,0]
	v_pk_fma_f32 v[8:9], v[94:95], v[12:13], v[50:51] op_sel_hi:[1,0,1] neg_lo:[1,0,0] neg_hi:[1,0,0]
	ds_read_b128 v[20:23], v10 offset:61696
	ds_read_b128 v[16:19], v10 offset:61440
	ds_read_b128 v[28:31], v10 offset:62208
	ds_read_b128 v[24:27], v10 offset:61952
	s_waitcnt lgkmcnt(5)
	v_fma_mix_f32 v12, v6, v110, v180 op_sel_hi:[0,1,0]
	v_fma_mix_f32 v12, v7, v110, v12 op_sel:[0,1,0] op_sel_hi:[0,1,0]
	v_fma_mix_f32 v12, v8, v111, v12 op_sel_hi:[0,1,0]
	v_fma_mix_f32 v12, v9, v111, v12 op_sel:[0,1,0] op_sel_hi:[0,1,0]
	v_pk_mul_f32 v[48:49], v[6:7], v[106:107]
	v_pk_mul_f32 v[50:51], v[8:9], v[108:109]
	v_add_f32_dpp v12, v12, v12 row_ror:1 row_mask:0xf bank_mask:0xf bound_ctrl:1
	v_pk_fma_f32 v[48:49], v[118:119], v[68:69], v[48:49] op_sel:[0,1,0]
	v_pk_fma_f32 v[50:51], v[120:121], v[68:69], v[50:51] op_sel:[0,1,0]
	v_add_f32_dpp v12, v12, v12 row_ror:2 row_mask:0xf bank_mask:0xf bound_ctrl:1
	v_fma_mix_f32 v101, v6, v90, v180 op_sel_hi:[0,1,0]
	v_fma_mix_f32 v101, v7, v90, v101 op_sel:[0,1,0] op_sel_hi:[0,1,0]
	v_add_f32_dpp v12, v12, v12 row_ror:4 row_mask:0xf bank_mask:0xf bound_ctrl:1
	v_fma_mix_f32 v101, v8, v91, v101 op_sel_hi:[0,1,0]
	v_fma_mix_f32 v101, v9, v91, v101 op_sel:[0,1,0] op_sel_hi:[0,1,0]
	v_add_f32_dpp v12, v12, v12 row_ror:8 row_mask:0xf bank_mask:0xf bound_ctrl:1
	v_pk_fma_f32 v[6:7], v[114:115], v[12:13], v[48:49] op_sel_hi:[1,0,1] neg_lo:[1,0,0] neg_hi:[1,0,0]
	v_pk_fma_f32 v[8:9], v[116:117], v[12:13], v[50:51] op_sel_hi:[1,0,1] neg_lo:[1,0,0] neg_hi:[1,0,0]
	ds_read_b128 v[36:39], v10 offset:62720
	ds_read_b128 v[32:35], v10 offset:62464
	ds_read_b128 v[44:47], v10 offset:63232
	ds_read_b128 v[40:43], v10 offset:62976
	s_waitcnt lgkmcnt(4)
	v_fma_mix_f32 v12, v6, v20, v180 op_sel_hi:[0,1,0]
	v_fma_mix_f32 v12, v7, v20, v12 op_sel:[0,1,0] op_sel_hi:[0,1,0]
	v_fma_mix_f32 v12, v8, v21, v12 op_sel_hi:[0,1,0]
	v_fma_mix_f32 v12, v9, v21, v12 op_sel:[0,1,0] op_sel_hi:[0,1,0]
	v_pk_mul_f32 v[48:49], v[6:7], v[16:17]
	v_pk_mul_f32 v[50:51], v[8:9], v[18:19]
	v_add_f32_dpp v12, v12, v12 row_ror:1 row_mask:0xf bank_mask:0xf bound_ctrl:1
	v_pk_fma_f32 v[48:49], v[28:29], v[70:71], v[48:49] op_sel_hi:[1,0,1]
	v_pk_fma_f32 v[50:51], v[30:31], v[70:71], v[50:51] op_sel_hi:[1,0,1]
	v_add_f32_dpp v12, v12, v12 row_ror:2 row_mask:0xf bank_mask:0xf bound_ctrl:1
	v_fma_mix_f32 v102, v6, v112, v180 op_sel_hi:[0,1,0]
	v_fma_mix_f32 v102, v7, v112, v102 op_sel:[0,1,0] op_sel_hi:[0,1,0]
	v_add_f32_dpp v12, v12, v12 row_ror:4 row_mask:0xf bank_mask:0xf bound_ctrl:1
	v_fma_mix_f32 v102, v8, v113, v102 op_sel_hi:[0,1,0]
	v_fma_mix_f32 v102, v9, v113, v102 op_sel:[0,1,0] op_sel_hi:[0,1,0]
	v_add_f32_dpp v12, v12, v12 row_ror:8 row_mask:0xf bank_mask:0xf bound_ctrl:1
	v_pk_fma_f32 v[6:7], v[24:25], v[12:13], v[48:49] op_sel_hi:[1,0,1] neg_lo:[1,0,0] neg_hi:[1,0,0]
	v_pk_fma_f32 v[8:9], v[26:27], v[12:13], v[50:51] op_sel_hi:[1,0,1] neg_lo:[1,0,0] neg_hi:[1,0,0]
	ds_read_b128 v[88:91], v10 offset:63744
	ds_read_b128 v[84:87], v10 offset:63488
	ds_read_b128 v[96:99], v10 offset:64256
	ds_read_b128 v[92:95], v10 offset:64000
	s_waitcnt lgkmcnt(4)
	v_fma_mix_f32 v12, v6, v36, v180 op_sel_hi:[0,1,0]
	v_fma_mix_f32 v12, v7, v36, v12 op_sel:[0,1,0] op_sel_hi:[0,1,0]
	v_fma_mix_f32 v12, v8, v37, v12 op_sel_hi:[0,1,0]
	v_fma_mix_f32 v12, v9, v37, v12 op_sel:[0,1,0] op_sel_hi:[0,1,0]
	v_pk_mul_f32 v[48:49], v[6:7], v[32:33]
	v_pk_mul_f32 v[50:51], v[8:9], v[34:35]
	v_add_f32_dpp v12, v12, v12 row_ror:1 row_mask:0xf bank_mask:0xf bound_ctrl:1
	v_pk_fma_f32 v[48:49], v[44:45], v[70:71], v[48:49] op_sel:[0,1,0]
	v_pk_fma_f32 v[50:51], v[46:47], v[70:71], v[50:51] op_sel:[0,1,0]
	v_add_f32_dpp v12, v12, v12 row_ror:2 row_mask:0xf bank_mask:0xf bound_ctrl:1
	v_fma_mix_f32 v103, v6, v22, v180 op_sel_hi:[0,1,0]
	v_fma_mix_f32 v103, v7, v22, v103 op_sel:[0,1,0] op_sel_hi:[0,1,0]
	v_add_f32_dpp v12, v12, v12 row_ror:4 row_mask:0xf bank_mask:0xf bound_ctrl:1
	v_fma_mix_f32 v103, v8, v23, v103 op_sel_hi:[0,1,0]
	v_fma_mix_f32 v103, v9, v23, v103 op_sel:[0,1,0] op_sel_hi:[0,1,0]
	v_add_f32_dpp v12, v12, v12 row_ror:8 row_mask:0xf bank_mask:0xf bound_ctrl:1
	v_pk_fma_f32 v[6:7], v[40:41], v[12:13], v[48:49] op_sel_hi:[1,0,1] neg_lo:[1,0,0] neg_hi:[1,0,0]
	v_pk_fma_f32 v[8:9], v[42:43], v[12:13], v[50:51] op_sel_hi:[1,0,1] neg_lo:[1,0,0] neg_hi:[1,0,0]
	ds_read_b128 v[110:113], v10 offset:64768
	ds_read_b128 v[106:109], v10 offset:64512
	ds_read_b128 v[118:121], v10 offset:65280
	ds_read_b128 v[114:117], v10 offset:65024
	s_waitcnt lgkmcnt(4)
	v_fma_mix_f32 v12, v6, v88, v180 op_sel_hi:[0,1,0]
	v_fma_mix_f32 v12, v7, v88, v12 op_sel:[0,1,0] op_sel_hi:[0,1,0]
	v_fma_mix_f32 v12, v8, v89, v12 op_sel_hi:[0,1,0]
	v_fma_mix_f32 v12, v9, v89, v12 op_sel:[0,1,0] op_sel_hi:[0,1,0]
	v_pk_mul_f32 v[48:49], v[6:7], v[84:85]
	v_pk_mul_f32 v[50:51], v[8:9], v[86:87]
	v_add_f32_dpp v12, v12, v12 row_ror:1 row_mask:0xf bank_mask:0xf bound_ctrl:1
	v_pk_fma_f32 v[48:49], v[96:97], v[72:73], v[48:49] op_sel_hi:[1,0,1]
	v_pk_fma_f32 v[50:51], v[98:99], v[72:73], v[50:51] op_sel_hi:[1,0,1]
	v_add_f32_dpp v12, v12, v12 row_ror:2 row_mask:0xf bank_mask:0xf bound_ctrl:1
	v_fma_mix_f32 v104, v6, v38, v180 op_sel_hi:[0,1,0]
	v_fma_mix_f32 v104, v7, v38, v104 op_sel:[0,1,0] op_sel_hi:[0,1,0]
	v_add_f32_dpp v12, v12, v12 row_ror:4 row_mask:0xf bank_mask:0xf bound_ctrl:1
	v_fma_mix_f32 v104, v8, v39, v104 op_sel_hi:[0,1,0]
	v_fma_mix_f32 v104, v9, v39, v104 op_sel:[0,1,0] op_sel_hi:[0,1,0]
	v_add_f32_dpp v12, v12, v12 row_ror:8 row_mask:0xf bank_mask:0xf bound_ctrl:1
	v_pk_fma_f32 v[6:7], v[92:93], v[12:13], v[48:49] op_sel_hi:[1,0,1] neg_lo:[1,0,0] neg_hi:[1,0,0]
	v_pk_fma_f32 v[8:9], v[94:95], v[12:13], v[50:51] op_sel_hi:[1,0,1] neg_lo:[1,0,0] neg_hi:[1,0,0]
	s_waitcnt lgkmcnt(0)
	s_barrier
	v_xor_b32_e32 v10, 0x10000, v10
	v_xor_b32_e32 v11, 0x1000, v11
	ds_read_b128 v[66:69], v11 offset:0
	ds_read_b128 v[20:23], v10 offset:256
	ds_read_b128 v[16:19], v10 offset:0
	ds_read_b128 v[28:31], v10 offset:768
	ds_read_b128 v[24:27], v10 offset:512
	ds_read_b128 v[36:39], v10 offset:1280
	ds_read_b128 v[32:35], v10 offset:1024
	ds_read_b128 v[44:47], v10 offset:1792
	ds_read_b128 v[40:43], v10 offset:1536
	v_fma_mix_f32 v12, v6, v110, v180 op_sel_hi:[0,1,0]
	v_fma_mix_f32 v12, v7, v110, v12 op_sel:[0,1,0] op_sel_hi:[0,1,0]
	v_fma_mix_f32 v12, v8, v111, v12 op_sel_hi:[0,1,0]
	v_fma_mix_f32 v12, v9, v111, v12 op_sel:[0,1,0] op_sel_hi:[0,1,0]
	v_pk_mul_f32 v[48:49], v[6:7], v[106:107]
	v_pk_mul_f32 v[50:51], v[8:9], v[108:109]
	v_add_f32_dpp v12, v12, v12 row_ror:1 row_mask:0xf bank_mask:0xf bound_ctrl:1
	v_pk_fma_f32 v[48:49], v[118:119], v[72:73], v[48:49] op_sel:[0,1,0]
	v_pk_fma_f32 v[50:51], v[120:121], v[72:73], v[50:51] op_sel:[0,1,0]
	v_add_f32_dpp v12, v12, v12 row_ror:2 row_mask:0xf bank_mask:0xf bound_ctrl:1
	v_fma_mix_f32 v105, v6, v90, v180 op_sel_hi:[0,1,0]
	v_fma_mix_f32 v105, v7, v90, v105 op_sel:[0,1,0] op_sel_hi:[0,1,0]
	v_add_f32_dpp v12, v12, v12 row_ror:4 row_mask:0xf bank_mask:0xf bound_ctrl:1
	v_fma_mix_f32 v105, v8, v91, v105 op_sel_hi:[0,1,0]
	v_fma_mix_f32 v105, v9, v91, v105 op_sel:[0,1,0] op_sel_hi:[0,1,0]
	v_add_f32_dpp v12, v12, v12 row_ror:8 row_mask:0xf bank_mask:0xf bound_ctrl:1
	v_pk_fma_f32 v[6:7], v[114:115], v[12:13], v[48:49] op_sel_hi:[1,0,1] neg_lo:[1,0,0] neg_hi:[1,0,0]
	v_pk_fma_f32 v[8:9], v[116:117], v[12:13], v[50:51] op_sel_hi:[1,0,1] neg_lo:[1,0,0] neg_hi:[1,0,0]
	v_fma_mix_f32 v61, v6, v112, v180 op_sel_hi:[0,1,0]
	v_fma_mix_f32 v61, v7, v112, v61 op_sel:[0,1,0] op_sel_hi:[0,1,0]
	v_fma_mix_f32 v61, v8, v113, v61 op_sel_hi:[0,1,0]
	v_fma_mix_f32 v61, v9, v113, v61 op_sel:[0,1,0] op_sel_hi:[0,1,0]
	v_add_f32_dpp v83, v83, v83 row_ror:8 row_mask:0xf bank_mask:0xc
	v_add_f32_dpp v83, v52, v52 row_ror:8 row_mask:0xf bank_mask:0x3
	v_add_f32_dpp v100, v100, v100 row_ror:8 row_mask:0xf bank_mask:0xc
	v_add_f32_dpp v100, v53, v53 row_ror:8 row_mask:0xf bank_mask:0x3
	v_add_f32_dpp v101, v101, v101 row_ror:8 row_mask:0xf bank_mask:0xc
	v_add_f32_dpp v101, v54, v54 row_ror:8 row_mask:0xf bank_mask:0x3
	v_add_f32_dpp v102, v102, v102 row_ror:8 row_mask:0xf bank_mask:0xc
	v_add_f32_dpp v102, v55, v55 row_ror:8 row_mask:0xf bank_mask:0x3
	v_add_f32_dpp v103, v103, v103 row_ror:8 row_mask:0xf bank_mask:0xc
	v_add_f32_dpp v103, v56, v56 row_ror:8 row_mask:0xf bank_mask:0x3
	v_add_f32_dpp v104, v104, v104 row_ror:8 row_mask:0xf bank_mask:0xc
	v_add_f32_dpp v104, v57, v57 row_ror:8 row_mask:0xf bank_mask:0x3
	v_add_f32_dpp v105, v105, v105 row_ror:8 row_mask:0xf bank_mask:0xc
	v_add_f32_dpp v105, v81, v81 row_ror:8 row_mask:0xf bank_mask:0x3
	v_add_f32_dpp v61, v61, v61 row_ror:8 row_mask:0xf bank_mask:0xc
	v_add_f32_dpp v61, v82, v82 row_ror:8 row_mask:0xf bank_mask:0x3
	v_add_f32_dpp v103, v103, v103 row_ror:4 row_mask:0xf bank_mask:0xa
	v_add_f32_dpp v103, v83, v83 row_ror:12 row_mask:0xf bank_mask:0x5
	v_add_f32_dpp v104, v104, v104 row_ror:4 row_mask:0xf bank_mask:0xa
	v_add_f32_dpp v104, v100, v100 row_ror:12 row_mask:0xf bank_mask:0x5
	v_add_f32_dpp v105, v105, v105 row_ror:4 row_mask:0xf bank_mask:0xa
	v_add_f32_dpp v105, v101, v101 row_ror:12 row_mask:0xf bank_mask:0x5
	v_add_f32_dpp v61, v61, v61 row_ror:4 row_mask:0xf bank_mask:0xa
	v_add_f32_dpp v61, v102, v102 row_ror:12 row_mask:0xf bank_mask:0x5
	v_cndmask_b32_e64 v62, v105, v103, s[38:39]
	v_cndmask_b32_e64 v63, v103, v105, s[38:39]
	v_cndmask_b32_e64 v64, v61, v104, s[38:39]
	v_cndmask_b32_e64 v65, v104, v61, s[38:39]
	v_add_f32_dpp v62, v63, v62 quad_perm:[2,3,0,1] row_mask:0xf bank_mask:0xf bound_ctrl:1
	s_nop 0
	v_add_f32_dpp v63, v65, v64 quad_perm:[2,3,0,1] row_mask:0xf bank_mask:0xf bound_ctrl:1
	v_cndmask_b32_e64 v65, v63, v62, s[40:41]
	v_cndmask_b32_e64 v62, v62, v63, s[40:41]
	s_nop 1
	v_add_f32_dpp v62, v62, v65 quad_perm:[1,0,3,2] row_mask:0xf bank_mask:0xf bound_ctrl:1
	v_cvt_pk_bf16_f32 v62, v62, v62
	global_store_short v[2:3], v62, off
	s_cmp_lg_u32 s28, 0x800000
	s_cbranch_scc1 .Lscan_cons_chunk
	s_branch .LBB0_53
